# strategy 7: phase-1 cross-row reduction steps (xor 16 / xor 32) via v_permlane16_swap / v_permlane32_swap instead of ds_bpermute round trips
# baseline (speedup 1.0000x reference)
.LBB0_83:
	s_waitcnt vmcnt(3) lgkmcnt(7)
	v_pk_mul_f32 v[214:215], v[8:9], v[8:9]
	s_waitcnt lgkmcnt(0)
	v_pk_mul_f32 v[216:217], v[6:7], v[6:7]
	s_waitcnt vmcnt(0)
	v_mul_f32_e32 v213, v10, v10
	s_waitcnt lgkmcnt(0)
	v_pk_mov_b32 v[218:219], v[216:217], v[214:215] op_sel:[1,0]
	v_mov_b32_e32 v217, v215
	v_pk_add_f32 v[214:215], v[218:219], v[216:217]
	v_pk_mul_f32 v[216:217], v[4:5], v[4:5]
	v_pk_mul_f32 v[218:219], v[2:3], v[2:3]
	v_pk_add_f32 v[214:215], v[214:215], v[214:215] op_sel:[0,1] op_sel_hi:[1,0]
	s_waitcnt lgkmcnt(0)
	v_pk_mov_b32 v[220:221], v[218:219], v[216:217] op_sel:[1,0]
	v_mov_b32_e32 v219, v217
	v_pk_add_f32 v[216:217], v[220:221], v[218:219]
	v_mul_f32_e32 v218, v11, v11
	v_pk_add_f32 v[216:217], v[216:217], v[216:217] op_sel:[0,1] op_sel_hi:[1,0]
	v_mov_b32_e32 v215, v213
	v_mov_b32_e32 v217, v218
	v_pk_add_f32 v[214:215], v[214:215], v[216:217]
	v_mul_f32_e32 v216, v15, v15
	v_mul_f32_e32 v219, v12, v12
	v_pk_fma_f32 v[216:217], v[14:15], v[14:15], v[216:217] op_sel_hi:[1,1,0]
	v_mul_f32_e32 v218, v17, v17
	v_mul_f32_e32 v220, v13, v13
	v_mov_b32_e32 v217, v219
	v_pk_fma_f32 v[218:219], v[16:17], v[16:17], v[218:219] op_sel_hi:[1,1,0]
	s_add_i32 s20, s29, s35
	v_mov_b32_e32 v219, v220
	v_pk_add_f32 v[216:217], v[216:217], v[218:219]
	s_ashr_i32 s21, s20, 31
	v_pk_add_f32 v[214:215], v[214:215], v[216:217]
	s_lshl_b64 s[4:5], s[20:21], 11
	v_add_f32_e32 v213, v214, v215
	s_nop 1
	v_add_f32_dpp v213, v213, v213 quad_perm:[1,0,3,2] row_mask:0xf bank_mask:0xf bound_ctrl:1
	s_nop 1
	v_add_f32_dpp v213, v213, v213 quad_perm:[2,3,0,1] row_mask:0xf bank_mask:0xf bound_ctrl:1
	s_nop 1
	v_add_f32_dpp v213, v213, v213 row_half_mirror row_mask:0xf bank_mask:0xf bound_ctrl:1
	s_nop 1
	v_add_f32_dpp v213, v213, v213 row_mirror row_mask:0xf bank_mask:0xf bound_ctrl:1
	v_mov_b32_e32 v214, v213
	s_nop 1
	v_permlane16_swap_b32_e32 v214, v213
	s_waitcnt lgkmcnt(0)
	v_add_f32_e32 v213, v213, v214
	v_mov_b32_e32 v214, v213
	s_nop 1
	v_permlane32_swap_b32_e32 v214, v213
	s_waitcnt lgkmcnt(0)
	v_add_f32_e32 v213, v213, v214
	v_fmamk_f32 v213, v213, 0x3a800000, v211
	v_rsq_f32_e32 v230, v213
	ds_read_b128 v[214:217], v210
	ds_read_b128 v[218:221], v210 offset:4096
	ds_read_b128 v[222:225], v210 offset:1024
	ds_read_b128 v[226:229], v210 offset:5120
	v_pk_mul_f32 v[6:7], v[6:7], v[230:231] op_sel_hi:[1,0]
	v_pk_mul_f32 v[8:9], v[8:9], v[230:231] op_sel_hi:[1,0]
	s_waitcnt lgkmcnt(0)
	v_pk_fma_f32 v[6:7], v[214:215], v[6:7], v[218:219]
	v_pk_fma_f32 v[8:9], v[216:217], v[8:9], v[220:221]
	ds_read_b128 v[214:217], v210 offset:2048
	ds_read_b128 v[218:221], v210 offset:6144
	v_pk_mul_f32 v[2:3], v[2:3], v[230:231] op_sel_hi:[1,0]
	v_pk_mul_f32 v[4:5], v[4:5], v[230:231] op_sel_hi:[1,0]
	s_waitcnt lgkmcnt(0)
	v_pk_fma_f32 v[2:3], v[222:223], v[2:3], v[226:227]
	v_pk_fma_f32 v[4:5], v[224:225], v[4:5], v[228:229]
	ds_read_b128 v[222:225], v210 offset:3072
	ds_read_b128 v[226:229], v210 offset:7168
	v_pk_mul_f32 v[14:15], v[14:15], v[230:231] op_sel_hi:[1,0]
	v_pk_mul_f32 v[16:17], v[16:17], v[230:231] op_sel_hi:[1,0]
	s_waitcnt lgkmcnt(0)
	v_pk_fma_f32 v[14:15], v[214:215], v[14:15], v[218:219]
	v_pk_fma_f32 v[16:17], v[216:217], v[16:17], v[220:221]
	v_lshl_add_u64 v[214:215], v[206:207], 0, s[4:5]
	v_cvt_pk_bf16_f32 v216, v6, v7
	v_cvt_pk_bf16_f32 v217, v8, v9
	v_pk_mul_f32 v[10:11], v[10:11], v[230:231] op_sel_hi:[1,0]
	v_pk_mul_f32 v[12:13], v[12:13], v[230:231] op_sel_hi:[1,0]
	global_store_dwordx2 v[214:215], v[216:217], off
	v_cvt_pk_bf16_f32 v216, v2, v3
	v_cvt_pk_bf16_f32 v217, v4, v5
	s_waitcnt lgkmcnt(0)
	v_pk_fma_f32 v[12:13], v[224:225], v[12:13], v[228:229]
	v_pk_fma_f32 v[10:11], v[222:223], v[10:11], v[226:227]
	global_store_dwordx2 v[214:215], v[216:217], off offset:512
	v_cvt_pk_bf16_f32 v216, v14, v15
	v_cvt_pk_bf16_f32 v217, v16, v17
	global_store_dwordx2 v[214:215], v[216:217], off offset:1024
	v_cvt_pk_bf16_f32 v216, v10, v11
	v_cvt_pk_bf16_f32 v217, v12, v13
	global_store_dwordx2 v[214:215], v[216:217], off offset:1536
	v_fma_f32 v213, v6, v162, 0
	v_fma_f32 v214, v7, v163, 0
	v_fmac_f32_e32 v213, v8, v164
	v_fmac_f32_e32 v214, v9, v165
	v_fmac_f32_e32 v213, v2, v158
	v_fmac_f32_e32 v214, v3, v159
	v_fmac_f32_e32 v213, v4, v160
	v_fmac_f32_e32 v214, v5, v161
	v_fmac_f32_e32 v213, v14, v154
	v_fmac_f32_e32 v214, v15, v155
	v_fmac_f32_e32 v213, v16, v156
	v_fmac_f32_e32 v214, v17, v157
	v_fmac_f32_e32 v213, v10, v150
	v_fmac_f32_e32 v214, v11, v151
	v_fmac_f32_e32 v213, v12, v152
	v_fmac_f32_e32 v214, v13, v153
	v_add_f32_e32 v213, v214, v213
	v_fma_f32 v214, v6, v146, 0
	v_fma_f32 v215, v7, v147, 0
	v_fmac_f32_e32 v214, v8, v148
	v_fmac_f32_e32 v215, v9, v149
	v_fmac_f32_e32 v214, v2, v142
	v_fmac_f32_e32 v215, v3, v143
	v_fmac_f32_e32 v214, v4, v144
	v_fmac_f32_e32 v215, v5, v145
	v_fmac_f32_e32 v214, v14, v138
	v_fmac_f32_e32 v215, v15, v139
	v_fmac_f32_e32 v214, v16, v140
	v_fmac_f32_e32 v215, v17, v141
	v_fmac_f32_e32 v214, v10, v134
	v_fmac_f32_e32 v215, v11, v135
	v_fmac_f32_e32 v214, v12, v136
	v_fmac_f32_e32 v215, v13, v137
	v_add_f32_e32 v214, v215, v214
	v_fma_f32 v216, v7, v131, 0
	v_fmac_f32_e32 v216, v9, v133
	v_add_f32_dpp v214, v214, v214 quad_perm:[1,0,3,2] row_mask:0xf bank_mask:0xf bound_ctrl:1
	v_fmac_f32_e32 v216, v3, v127
	v_fmac_f32_e32 v216, v5, v129
	v_add_f32_dpp v214, v214, v214 quad_perm:[2,3,0,1] row_mask:0xf bank_mask:0xf bound_ctrl:1
	v_fmac_f32_e32 v216, v15, v123
	v_fmac_f32_e32 v216, v17, v125
	v_add_f32_dpp v214, v214, v214 row_half_mirror row_mask:0xf bank_mask:0xf bound_ctrl:1
	v_fmac_f32_e32 v216, v11, v119
	v_fmac_f32_e32 v216, v13, v121
	v_add_f32_dpp v215, v214, v214 row_mirror row_mask:0xf bank_mask:0xf bound_ctrl:1
	v_fma_f32 v214, v6, v130, 0
	v_fmac_f32_e32 v214, v8, v132
	v_fmac_f32_e32 v214, v2, v126
	v_fmac_f32_e32 v214, v4, v128
	v_fmac_f32_e32 v214, v14, v122
	v_fmac_f32_e32 v214, v16, v124
	v_fmac_f32_e32 v214, v10, v118
	v_fmac_f32_e32 v214, v12, v120
	v_add_f32_e32 v214, v216, v214
	v_fma_f32 v216, v7, v115, 0
	v_fmac_f32_e32 v216, v9, v117
	v_add_f32_dpp v214, v214, v214 quad_perm:[1,0,3,2] row_mask:0xf bank_mask:0xf bound_ctrl:1
	v_fmac_f32_e32 v216, v3, v111
	v_fmac_f32_e32 v216, v5, v113
	v_add_f32_dpp v214, v214, v214 quad_perm:[2,3,0,1] row_mask:0xf bank_mask:0xf bound_ctrl:1
	v_fmac_f32_e32 v216, v15, v107
	v_fmac_f32_e32 v216, v17, v109
	v_add_f32_dpp v214, v214, v214 row_half_mirror row_mask:0xf bank_mask:0xf bound_ctrl:1
	v_fmac_f32_e32 v216, v11, v103
	v_fmac_f32_e32 v216, v13, v105
	v_add_f32_dpp v217, v214, v214 row_mirror row_mask:0xf bank_mask:0xf bound_ctrl:1
	v_fma_f32 v214, v6, v114, 0
	v_fmac_f32_e32 v214, v8, v116
	v_fmac_f32_e32 v214, v2, v110
	v_fmac_f32_e32 v214, v4, v112
	v_fmac_f32_e32 v214, v14, v106
	v_fmac_f32_e32 v214, v16, v108
	v_fmac_f32_e32 v214, v10, v102
	v_fmac_f32_e32 v214, v12, v104
	v_add_f32_e32 v214, v216, v214
	v_fma_f32 v216, v7, v99, 0
	v_fmac_f32_e32 v216, v9, v101
	v_add_f32_dpp v214, v214, v214 quad_perm:[1,0,3,2] row_mask:0xf bank_mask:0xf bound_ctrl:1
	v_fmac_f32_e32 v216, v3, v95
	v_fmac_f32_e32 v216, v5, v97
	v_add_f32_dpp v214, v214, v214 quad_perm:[2,3,0,1] row_mask:0xf bank_mask:0xf bound_ctrl:1
	v_fmac_f32_e32 v216, v15, v91
	v_fmac_f32_e32 v216, v17, v93
	v_add_f32_dpp v214, v214, v214 row_half_mirror row_mask:0xf bank_mask:0xf bound_ctrl:1
	v_fmac_f32_e32 v216, v11, v87
	v_fmac_f32_e32 v216, v13, v89
	v_add_f32_dpp v219, v214, v214 row_mirror row_mask:0xf bank_mask:0xf bound_ctrl:1
	v_fma_f32 v214, v6, v98, 0
	v_fmac_f32_e32 v214, v8, v100
	v_fmac_f32_e32 v214, v2, v94
	v_fmac_f32_e32 v214, v4, v96
	v_fmac_f32_e32 v214, v14, v90
	v_fmac_f32_e32 v214, v16, v92
	v_fmac_f32_e32 v214, v10, v86
	v_fmac_f32_e32 v214, v12, v88
	v_add_f32_e32 v214, v216, v214
	v_fma_f32 v216, v7, v83, 0
	v_fmac_f32_e32 v216, v9, v85
	v_add_f32_dpp v214, v214, v214 quad_perm:[1,0,3,2] row_mask:0xf bank_mask:0xf bound_ctrl:1
	v_fmac_f32_e32 v216, v3, v79
	v_fmac_f32_e32 v216, v5, v81
	v_add_f32_dpp v214, v214, v214 quad_perm:[2,3,0,1] row_mask:0xf bank_mask:0xf bound_ctrl:1
	v_fmac_f32_e32 v216, v15, v75
	v_fmac_f32_e32 v216, v17, v77
	v_add_f32_dpp v214, v214, v214 row_half_mirror row_mask:0xf bank_mask:0xf bound_ctrl:1
	v_fmac_f32_e32 v216, v11, v71
	v_fmac_f32_e32 v216, v13, v73
	v_add_f32_dpp v221, v214, v214 row_mirror row_mask:0xf bank_mask:0xf bound_ctrl:1
	v_fma_f32 v214, v6, v82, 0
	v_fmac_f32_e32 v214, v8, v84
	v_fmac_f32_e32 v214, v2, v78
	v_fmac_f32_e32 v214, v4, v80
	v_fmac_f32_e32 v214, v14, v74
	v_fmac_f32_e32 v214, v16, v76
	v_fmac_f32_e32 v214, v10, v70
	v_fmac_f32_e32 v214, v12, v72
	v_add_f32_e32 v214, v216, v214
	v_fma_f32 v216, v7, v67, 0
	v_fmac_f32_e32 v216, v9, v69
	v_add_f32_dpp v214, v214, v214 quad_perm:[1,0,3,2] row_mask:0xf bank_mask:0xf bound_ctrl:1
	v_fmac_f32_e32 v216, v3, v63
	v_fmac_f32_e32 v216, v5, v65
	v_add_f32_dpp v214, v214, v214 quad_perm:[2,3,0,1] row_mask:0xf bank_mask:0xf bound_ctrl:1
	v_fmac_f32_e32 v216, v15, v59
	v_fmac_f32_e32 v216, v17, v61
	v_add_f32_dpp v214, v214, v214 row_half_mirror row_mask:0xf bank_mask:0xf bound_ctrl:1
	v_fmac_f32_e32 v216, v11, v55
	v_fmac_f32_e32 v216, v13, v57
	v_add_f32_dpp v223, v214, v214 row_mirror row_mask:0xf bank_mask:0xf bound_ctrl:1
	v_fma_f32 v214, v6, v66, 0
	v_fmac_f32_e32 v214, v8, v68
	v_fmac_f32_e32 v214, v2, v62
	v_fmac_f32_e32 v214, v4, v64
	v_fmac_f32_e32 v214, v14, v58
	v_fmac_f32_e32 v214, v16, v60
	v_fmac_f32_e32 v214, v10, v54
	v_fmac_f32_e32 v214, v12, v56
	v_add_f32_e32 v214, v216, v214
	v_fma_f32 v216, v7, v51, 0
	v_fmac_f32_e32 v216, v9, v53
	v_add_f32_dpp v214, v214, v214 quad_perm:[1,0,3,2] row_mask:0xf bank_mask:0xf bound_ctrl:1
	v_fmac_f32_e32 v216, v3, v47
	v_fmac_f32_e32 v216, v5, v49
	v_add_f32_dpp v214, v214, v214 quad_perm:[2,3,0,1] row_mask:0xf bank_mask:0xf bound_ctrl:1
	v_fmac_f32_e32 v216, v15, v43
	v_fmac_f32_e32 v216, v17, v45
	v_add_f32_dpp v214, v214, v214 row_half_mirror row_mask:0xf bank_mask:0xf bound_ctrl:1
	v_fmac_f32_e32 v216, v11, v39
	v_fmac_f32_e32 v216, v13, v41
	v_add_f32_dpp v225, v214, v214 row_mirror row_mask:0xf bank_mask:0xf bound_ctrl:1
	v_fma_f32 v214, v6, v50, 0
	v_fmac_f32_e32 v214, v8, v52
	v_fmac_f32_e32 v214, v2, v46
	v_fmac_f32_e32 v214, v4, v48
	v_fmac_f32_e32 v214, v14, v42
	v_fmac_f32_e32 v214, v16, v44
	v_fmac_f32_e32 v214, v10, v38
	v_fmac_f32_e32 v214, v12, v40
	v_add_f32_e32 v214, v216, v214
	v_add_f32_dpp v213, v213, v213 quad_perm:[1,0,3,2] row_mask:0xf bank_mask:0xf bound_ctrl:1
	v_mov_b32_e32 v218, v215
	s_nop 1
	v_permlane16_swap_b32_e32 v218, v215
	v_add_f32_dpp v214, v214, v214 quad_perm:[1,0,3,2] row_mask:0xf bank_mask:0xf bound_ctrl:1
	v_add_f32_dpp v213, v213, v213 quad_perm:[2,3,0,1] row_mask:0xf bank_mask:0xf bound_ctrl:1
	v_mov_b32_e32 v220, v217
	s_nop 1
	v_permlane16_swap_b32_e32 v220, v217
	v_add_f32_dpp v214, v214, v214 quad_perm:[2,3,0,1] row_mask:0xf bank_mask:0xf bound_ctrl:1
	v_add_f32_dpp v213, v213, v213 row_half_mirror row_mask:0xf bank_mask:0xf bound_ctrl:1
	v_mov_b32_e32 v222, v219
	s_nop 1
	v_permlane16_swap_b32_e32 v222, v219
	v_add_f32_dpp v214, v214, v214 row_half_mirror row_mask:0xf bank_mask:0xf bound_ctrl:1
	v_add_f32_dpp v213, v213, v213 row_mirror row_mask:0xf bank_mask:0xf bound_ctrl:1
	v_mov_b32_e32 v216, v213
	s_nop 1
	v_permlane16_swap_b32_e32 v216, v213
	v_add_f32_dpp v227, v214, v214 row_mirror row_mask:0xf bank_mask:0xf bound_ctrl:1
	v_mov_b32_e32 v224, v221
	s_nop 1
	v_permlane16_swap_b32_e32 v224, v221
	v_mov_b32_e32 v226, v223
	s_nop 1
	v_permlane16_swap_b32_e32 v226, v223
	v_mov_b32_e32 v228, v225
	s_nop 1
	v_permlane16_swap_b32_e32 v228, v225
	v_mov_b32_e32 v229, v227
	s_nop 1
	v_permlane16_swap_b32_e32 v229, v227
	s_waitcnt lgkmcnt(0)
	v_add_f32_e32 v213, v213, v216
	v_add_f32_e32 v215, v215, v218
	v_add_f32_e32 v217, v217, v220
	v_add_f32_e32 v219, v219, v222
	s_waitcnt lgkmcnt(0)
	v_add_f32_e32 v221, v221, v224
	s_waitcnt lgkmcnt(0)
	v_add_f32_e32 v223, v223, v226
	s_waitcnt lgkmcnt(0)
	v_add_f32_e32 v225, v225, v228
	s_waitcnt lgkmcnt(0)
	v_add_f32_e32 v227, v227, v229
	v_mov_b32_e32 v214, v213
	s_nop 1
	v_permlane32_swap_b32_e32 v214, v213
	v_mov_b32_e32 v216, v215
	s_nop 1
	v_permlane32_swap_b32_e32 v216, v215
	v_mov_b32_e32 v218, v217
	s_nop 1
	v_permlane32_swap_b32_e32 v218, v217
	v_mov_b32_e32 v220, v219
	s_nop 1
	v_permlane32_swap_b32_e32 v220, v219
	v_mov_b32_e32 v222, v221
	s_nop 1
	v_permlane32_swap_b32_e32 v222, v221
	v_mov_b32_e32 v224, v223
	s_nop 1
	v_permlane32_swap_b32_e32 v224, v223
	v_mov_b32_e32 v226, v225
	s_nop 1
	v_permlane32_swap_b32_e32 v226, v225
	v_mov_b32_e32 v228, v227
	s_nop 1
	v_permlane32_swap_b32_e32 v228, v227
	s_and_saveexec_b64 s[22:23], s[2:3]
	s_cbranch_execz .LBB0_85
	s_waitcnt lgkmcnt(0)
	v_add_f32_e32 v227, v227, v228
	v_add_f32_e32 v225, v225, v226
	s_waitcnt vmcnt(4)
	v_add_f32_e32 v226, v37, v227
	v_mul_f32_e64 v227, |v226|, s30
	v_exp_f32_e32 v227, v227
	v_add_f32_e32 v221, v221, v222
	v_add_f32_e32 v222, v219, v220
	v_add_f32_e32 v213, v213, v214
	v_add_f32_e32 v219, 1.0, v227
	v_cmp_gt_f32_e32 vcc, s31, v219
	v_add_f32_e32 v227, v215, v216
	v_add_f32_e32 v216, v36, v225
	v_cndmask_b32_e64 v220, 0, 32, vcc
	v_ldexp_f32 v219, v219, v220
	v_log_f32_e32 v219, v219
	v_mul_f32_e64 v215, |v216|, s30
	v_exp_f32_e32 v215, v215
	v_add_f32_e32 v223, v223, v224
	v_mul_f32_e32 v214, 0x3f317217, v219
	v_fma_f32 v214, v219, s33, -v214
	v_fmac_f32_e32 v214, 0x3377d1cf, v219
	v_fmac_f32_e32 v214, 0x3f317217, v219
	v_cmp_lt_f32_e64 s[4:5], |v219|, s34
	v_add_f32_e32 v215, 1.0, v215
	v_add_f32_e32 v224, v217, v218
	v_cndmask_b32_e64 v214, v219, v214, s[4:5]
	v_cmp_gt_f32_e64 s[4:5], s31, v215
	v_add_f32_e32 v220, v35, v223
	v_mul_f32_e64 v219, |v220|, s30
	v_cndmask_b32_e64 v217, 0, 32, s[4:5]
	v_ldexp_f32 v215, v215, v217
	v_log_f32_e32 v218, v215
	v_cndmask_b32_e32 v215, 0, v212, vcc
	v_sub_f32_e32 v215, v214, v215
	v_exp_f32_e32 v219, v219
	v_mul_f32_e32 v214, 0x3f317217, v218
	v_fma_f32 v214, v218, s33, -v214
	v_fmac_f32_e32 v214, 0x3377d1cf, v218
	v_fmac_f32_e32 v214, 0x3f317217, v218
	v_cmp_lt_f32_e64 vcc, |v218|, s34
	v_add_f32_e32 v223, v34, v221
	v_mul_f32_e64 v221, |v223|, s30
	v_cndmask_b32_e32 v214, v218, v214, vcc
	v_add_f32_e32 v218, 1.0, v219
	v_cmp_gt_f32_e32 vcc, s31, v218
	v_exp_f32_e32 v221, v221
	v_mul_f32_e32 v213, 0xbfb8aa3b, v213
	v_cndmask_b32_e64 v219, 0, 32, vcc
	v_ldexp_f32 v218, v218, v219
	v_log_f32_e32 v218, v218
	v_cndmask_b32_e64 v219, 0, v212, s[4:5]
	v_sub_f32_e32 v214, v214, v219
	v_exp_f32_e32 v213, v213
	v_mul_f32_e32 v219, 0x3f317217, v218
	v_fma_f32 v219, v218, s33, -v219
	v_fmac_f32_e32 v219, 0x3377d1cf, v218
	v_fmac_f32_e32 v219, 0x3f317217, v218
	v_cmp_lt_f32_e64 s[4:5], |v218|, s34
	v_mul_f32_e32 v222, 0xbfb8aa3b, v222
	v_max_f32_e32 v217, 0, v226
	v_cndmask_b32_e64 v218, v218, v219, s[4:5]
	v_add_f32_e32 v219, 1.0, v221
	v_cmp_gt_f32_e64 s[4:5], s31, v219
	v_max_f32_e32 v216, 0, v216
	v_exp_f32_e32 v222, v222
	v_cndmask_b32_e64 v221, 0, 32, s[4:5]
	v_ldexp_f32 v219, v219, v221
	v_log_f32_e32 v225, v219
	v_cndmask_b32_e32 v219, 0, v212, vcc
	v_sub_f32_e32 v219, v218, v219
	v_max_f32_e32 v221, 0, v220
	v_mul_f32_e32 v218, 0x3f317217, v225
	v_fma_f32 v218, v225, s33, -v218
	v_fmac_f32_e32 v218, 0x3377d1cf, v225
	v_fmac_f32_e32 v218, 0x3f317217, v225
	v_cmp_lt_f32_e64 vcc, |v225|, s34
	v_cndmask_b32_e64 v220, 0, v212, s[4:5]
	v_pk_add_f32 v[214:215], v[216:217], v[214:215]
	v_cndmask_b32_e32 v218, v225, v218, vcc
	v_sub_f32_e32 v218, v218, v220
	v_max_f32_e32 v220, 0, v223
	v_mul_f32_e32 v223, 0xbfb8aa3b, v224
	v_mul_f32_e32 v224, 0xbfb8aa3b, v227
	v_exp_f32_e32 v224, v224
	v_exp_f32_e32 v223, v223
	v_pk_add_f32 v[218:219], v[220:221], v[218:219]
	v_add_f32_e32 v213, 1.0, v213
	v_pk_mul_f32 v[216:217], v[214:215], s[10:11]
	v_pk_mul_f32 v[214:215], v[218:219], s[8:9] neg_lo:[0,1] neg_hi:[0,1]
	v_rcp_f32_e32 v218, v213
	v_add_f32_e32 v213, 1.0, v224
	v_rcp_f32_e32 v219, v213
	v_add_f32_e32 v213, 1.0, v223
	v_rcp_f32_e32 v220, v213
	v_add_f32_e32 v213, 1.0, v222
	s_lshl_b64 s[4:5], s[20:21], 4
	v_rcp_f32_e32 v221, v213
	s_add_u32 s20, s24, s4
	s_addc_u32 s21, s25, s5
	s_add_u32 s4, s26, s4
	s_addc_u32 s5, s27, s5
	global_store_dwordx4 v201, v[218:221], s[20:21] sc1
	global_store_dwordx4 v201, v[214:217], s[4:5] sc1

.LBB0_90:
	s_waitcnt lgkmcnt(0)
	v_pk_mul_f32 v[214:215], v[24:25], v[24:25]
	s_waitcnt lgkmcnt(0)
	v_pk_mul_f32 v[216:217], v[22:23], v[22:23]
	v_mul_f32_e32 v213, v26, v26
	s_waitcnt lgkmcnt(0)
	v_pk_mov_b32 v[218:219], v[216:217], v[214:215] op_sel:[1,0]
	v_mov_b32_e32 v217, v215
	v_pk_add_f32 v[214:215], v[218:219], v[216:217]
	v_pk_mul_f32 v[216:217], v[20:21], v[20:21]
	v_pk_mul_f32 v[218:219], v[18:19], v[18:19]
	v_pk_add_f32 v[214:215], v[214:215], v[214:215] op_sel:[0,1] op_sel_hi:[1,0]
	s_waitcnt lgkmcnt(0)
	v_pk_mov_b32 v[220:221], v[218:219], v[216:217] op_sel:[1,0]
	v_mov_b32_e32 v219, v217
	v_pk_add_f32 v[216:217], v[220:221], v[218:219]
	v_mul_f32_e32 v218, v27, v27
	v_pk_add_f32 v[216:217], v[216:217], v[216:217] op_sel:[0,1] op_sel_hi:[1,0]
	v_mov_b32_e32 v215, v213
	v_mov_b32_e32 v217, v218
	v_pk_add_f32 v[214:215], v[214:215], v[216:217]
	v_mul_f32_e32 v216, v31, v31
	v_mul_f32_e32 v219, v28, v28
	v_pk_fma_f32 v[216:217], v[30:31], v[30:31], v[216:217] op_sel_hi:[1,1,0]
	v_mul_f32_e32 v218, v33, v33
	v_mul_f32_e32 v220, v29, v29
	v_mov_b32_e32 v217, v219
	v_pk_fma_f32 v[218:219], v[32:33], v[32:33], v[218:219] op_sel_hi:[1,1,0]
	s_ashr_i32 s21, s20, 31
	v_mov_b32_e32 v219, v220
	v_pk_add_f32 v[216:217], v[216:217], v[218:219]
	s_lshl_b64 s[4:5], s[20:21], 11
	v_pk_add_f32 v[214:215], v[214:215], v[216:217]
	s_nop 0
	v_add_f32_e32 v213, v214, v215
	s_nop 1
	v_add_f32_dpp v213, v213, v213 quad_perm:[1,0,3,2] row_mask:0xf bank_mask:0xf bound_ctrl:1
	s_nop 1
	v_add_f32_dpp v213, v213, v213 quad_perm:[2,3,0,1] row_mask:0xf bank_mask:0xf bound_ctrl:1
	s_nop 1
	v_add_f32_dpp v213, v213, v213 row_half_mirror row_mask:0xf bank_mask:0xf bound_ctrl:1
	s_nop 1
	v_add_f32_dpp v213, v213, v213 row_mirror row_mask:0xf bank_mask:0xf bound_ctrl:1
	v_mov_b32_e32 v214, v213
	s_nop 1
	v_permlane16_swap_b32_e32 v214, v213
	s_waitcnt lgkmcnt(0)
	v_add_f32_e32 v213, v213, v214
	v_mov_b32_e32 v214, v213
	s_nop 1
	v_permlane32_swap_b32_e32 v214, v213
	s_waitcnt lgkmcnt(0)
	v_add_f32_e32 v213, v213, v214
	v_fmamk_f32 v213, v213, 0x3a800000, v211
	v_rsq_f32_e32 v230, v213
	ds_read_b128 v[214:217], v210
	ds_read_b128 v[218:221], v210 offset:4096
	ds_read_b128 v[222:225], v210 offset:1024
	ds_read_b128 v[226:229], v210 offset:5120
	v_pk_mul_f32 v[22:23], v[22:23], v[230:231] op_sel_hi:[1,0]
	v_pk_mul_f32 v[24:25], v[24:25], v[230:231] op_sel_hi:[1,0]
	s_waitcnt lgkmcnt(0)
	v_pk_fma_f32 v[22:23], v[214:215], v[22:23], v[218:219]
	v_pk_fma_f32 v[24:25], v[216:217], v[24:25], v[220:221]
	ds_read_b128 v[214:217], v210 offset:2048
	ds_read_b128 v[218:221], v210 offset:6144
	v_pk_mul_f32 v[18:19], v[18:19], v[230:231] op_sel_hi:[1,0]
	v_pk_mul_f32 v[20:21], v[20:21], v[230:231] op_sel_hi:[1,0]
	s_waitcnt lgkmcnt(0)
	v_pk_fma_f32 v[18:19], v[222:223], v[18:19], v[226:227]
	v_pk_fma_f32 v[20:21], v[224:225], v[20:21], v[228:229]
	ds_read_b128 v[222:225], v210 offset:3072
	ds_read_b128 v[226:229], v210 offset:7168
	v_pk_mul_f32 v[30:31], v[30:31], v[230:231] op_sel_hi:[1,0]
	v_pk_mul_f32 v[32:33], v[32:33], v[230:231] op_sel_hi:[1,0]
	s_waitcnt lgkmcnt(0)
	v_pk_fma_f32 v[30:31], v[214:215], v[30:31], v[218:219]
	v_pk_fma_f32 v[32:33], v[216:217], v[32:33], v[220:221]
	v_lshl_add_u64 v[214:215], v[206:207], 0, s[4:5]
	v_cvt_pk_bf16_f32 v216, v22, v23
	v_cvt_pk_bf16_f32 v217, v24, v25
	v_pk_mul_f32 v[26:27], v[26:27], v[230:231] op_sel_hi:[1,0]
	v_pk_mul_f32 v[28:29], v[28:29], v[230:231] op_sel_hi:[1,0]
	global_store_dwordx2 v[214:215], v[216:217], off
	v_cvt_pk_bf16_f32 v216, v18, v19
	v_cvt_pk_bf16_f32 v217, v20, v21
	s_waitcnt lgkmcnt(0)
	v_pk_fma_f32 v[28:29], v[224:225], v[28:29], v[228:229]
	v_pk_fma_f32 v[26:27], v[222:223], v[26:27], v[226:227]
	global_store_dwordx2 v[214:215], v[216:217], off offset:512
	v_cvt_pk_bf16_f32 v216, v30, v31
	v_cvt_pk_bf16_f32 v217, v32, v33
	global_store_dwordx2 v[214:215], v[216:217], off offset:1024
	v_cvt_pk_bf16_f32 v216, v26, v27
	v_cvt_pk_bf16_f32 v217, v28, v29
	global_store_dwordx2 v[214:215], v[216:217], off offset:1536
	v_fma_f32 v213, v22, v162, 0
	v_fma_f32 v214, v23, v163, 0
	v_fmac_f32_e32 v213, v24, v164
	v_fmac_f32_e32 v214, v25, v165
	v_fmac_f32_e32 v213, v18, v158
	v_fmac_f32_e32 v214, v19, v159
	v_fmac_f32_e32 v213, v20, v160
	v_fmac_f32_e32 v214, v21, v161
	v_fmac_f32_e32 v213, v30, v154
	v_fmac_f32_e32 v214, v31, v155
	v_fmac_f32_e32 v213, v32, v156
	v_fmac_f32_e32 v214, v33, v157
	v_fmac_f32_e32 v213, v26, v150
	v_fmac_f32_e32 v214, v27, v151
	v_fmac_f32_e32 v213, v28, v152
	v_fmac_f32_e32 v214, v29, v153
	v_add_f32_e32 v213, v214, v213
	v_fma_f32 v214, v22, v146, 0
	v_fma_f32 v215, v23, v147, 0
	v_fmac_f32_e32 v214, v24, v148
	v_fmac_f32_e32 v215, v25, v149
	v_fmac_f32_e32 v214, v18, v142
	v_fmac_f32_e32 v215, v19, v143
	v_fmac_f32_e32 v214, v20, v144
	v_fmac_f32_e32 v215, v21, v145
	v_fmac_f32_e32 v214, v30, v138
	v_fmac_f32_e32 v215, v31, v139
	v_fmac_f32_e32 v214, v32, v140
	v_fmac_f32_e32 v215, v33, v141
	v_fmac_f32_e32 v214, v26, v134
	v_fmac_f32_e32 v215, v27, v135
	v_fmac_f32_e32 v214, v28, v136
	v_fmac_f32_e32 v215, v29, v137
	v_add_f32_e32 v214, v215, v214
	v_fma_f32 v216, v23, v131, 0
	v_fmac_f32_e32 v216, v25, v133
	v_add_f32_dpp v214, v214, v214 quad_perm:[1,0,3,2] row_mask:0xf bank_mask:0xf bound_ctrl:1
	v_fmac_f32_e32 v216, v19, v127
	v_fmac_f32_e32 v216, v21, v129
	v_add_f32_dpp v214, v214, v214 quad_perm:[2,3,0,1] row_mask:0xf bank_mask:0xf bound_ctrl:1
	v_fmac_f32_e32 v216, v31, v123
	v_fmac_f32_e32 v216, v33, v125
	v_add_f32_dpp v214, v214, v214 row_half_mirror row_mask:0xf bank_mask:0xf bound_ctrl:1
	v_fmac_f32_e32 v216, v27, v119
	v_fmac_f32_e32 v216, v29, v121
	v_add_f32_dpp v215, v214, v214 row_mirror row_mask:0xf bank_mask:0xf bound_ctrl:1
	v_fma_f32 v214, v22, v130, 0
	v_fmac_f32_e32 v214, v24, v132
	v_fmac_f32_e32 v214, v18, v126
	v_fmac_f32_e32 v214, v20, v128
	v_fmac_f32_e32 v214, v30, v122
	v_fmac_f32_e32 v214, v32, v124
	v_fmac_f32_e32 v214, v26, v118
	v_fmac_f32_e32 v214, v28, v120
	v_add_f32_e32 v214, v216, v214
	v_fma_f32 v216, v23, v115, 0
	v_fmac_f32_e32 v216, v25, v117
	v_add_f32_dpp v214, v214, v214 quad_perm:[1,0,3,2] row_mask:0xf bank_mask:0xf bound_ctrl:1
	v_fmac_f32_e32 v216, v19, v111
	v_fmac_f32_e32 v216, v21, v113
	v_add_f32_dpp v214, v214, v214 quad_perm:[2,3,0,1] row_mask:0xf bank_mask:0xf bound_ctrl:1
	v_fmac_f32_e32 v216, v31, v107
	v_fmac_f32_e32 v216, v33, v109
	v_add_f32_dpp v214, v214, v214 row_half_mirror row_mask:0xf bank_mask:0xf bound_ctrl:1
	v_fmac_f32_e32 v216, v27, v103
	v_fmac_f32_e32 v216, v29, v105
	v_add_f32_dpp v217, v214, v214 row_mirror row_mask:0xf bank_mask:0xf bound_ctrl:1
	v_fma_f32 v214, v22, v114, 0
	v_fmac_f32_e32 v214, v24, v116
	v_fmac_f32_e32 v214, v18, v110
	v_fmac_f32_e32 v214, v20, v112
	v_fmac_f32_e32 v214, v30, v106
	v_fmac_f32_e32 v214, v32, v108
	v_fmac_f32_e32 v214, v26, v102
	v_fmac_f32_e32 v214, v28, v104
	v_add_f32_e32 v214, v216, v214
	v_fma_f32 v216, v23, v99, 0
	v_fmac_f32_e32 v216, v25, v101
	v_add_f32_dpp v214, v214, v214 quad_perm:[1,0,3,2] row_mask:0xf bank_mask:0xf bound_ctrl:1
	v_fmac_f32_e32 v216, v19, v95
	v_fmac_f32_e32 v216, v21, v97
	v_add_f32_dpp v214, v214, v214 quad_perm:[2,3,0,1] row_mask:0xf bank_mask:0xf bound_ctrl:1
	v_fmac_f32_e32 v216, v31, v91
	v_fmac_f32_e32 v216, v33, v93
	v_add_f32_dpp v214, v214, v214 row_half_mirror row_mask:0xf bank_mask:0xf bound_ctrl:1
	v_fmac_f32_e32 v216, v27, v87
	v_fmac_f32_e32 v216, v29, v89
	v_add_f32_dpp v219, v214, v214 row_mirror row_mask:0xf bank_mask:0xf bound_ctrl:1
	v_fma_f32 v214, v22, v98, 0
	v_fmac_f32_e32 v214, v24, v100
	v_fmac_f32_e32 v214, v18, v94
	v_fmac_f32_e32 v214, v20, v96
	v_fmac_f32_e32 v214, v30, v90
	v_fmac_f32_e32 v214, v32, v92
	v_fmac_f32_e32 v214, v26, v86
	v_fmac_f32_e32 v214, v28, v88
	v_add_f32_e32 v214, v216, v214
	v_fma_f32 v216, v23, v83, 0
	v_fmac_f32_e32 v216, v25, v85
	v_add_f32_dpp v214, v214, v214 quad_perm:[1,0,3,2] row_mask:0xf bank_mask:0xf bound_ctrl:1
	v_fmac_f32_e32 v216, v19, v79
	v_fmac_f32_e32 v216, v21, v81
	v_add_f32_dpp v214, v214, v214 quad_perm:[2,3,0,1] row_mask:0xf bank_mask:0xf bound_ctrl:1
	v_fmac_f32_e32 v216, v31, v75
	v_fmac_f32_e32 v216, v33, v77
	v_add_f32_dpp v214, v214, v214 row_half_mirror row_mask:0xf bank_mask:0xf bound_ctrl:1
	v_fmac_f32_e32 v216, v27, v71
	v_fmac_f32_e32 v216, v29, v73
	v_add_f32_dpp v221, v214, v214 row_mirror row_mask:0xf bank_mask:0xf bound_ctrl:1
	v_fma_f32 v214, v22, v82, 0
	v_fmac_f32_e32 v214, v24, v84
	v_fmac_f32_e32 v214, v18, v78
	v_fmac_f32_e32 v214, v20, v80
	v_fmac_f32_e32 v214, v30, v74
	v_fmac_f32_e32 v214, v32, v76
	v_fmac_f32_e32 v214, v26, v70
	v_fmac_f32_e32 v214, v28, v72
	v_add_f32_e32 v214, v216, v214
	v_fma_f32 v216, v23, v67, 0
	v_fmac_f32_e32 v216, v25, v69
	v_add_f32_dpp v214, v214, v214 quad_perm:[1,0,3,2] row_mask:0xf bank_mask:0xf bound_ctrl:1
	v_fmac_f32_e32 v216, v19, v63
	v_fmac_f32_e32 v216, v21, v65
	v_add_f32_dpp v214, v214, v214 quad_perm:[2,3,0,1] row_mask:0xf bank_mask:0xf bound_ctrl:1
	v_fmac_f32_e32 v216, v31, v59
	v_fmac_f32_e32 v216, v33, v61
	v_add_f32_dpp v214, v214, v214 row_half_mirror row_mask:0xf bank_mask:0xf bound_ctrl:1
	v_fmac_f32_e32 v216, v27, v55
	v_fmac_f32_e32 v216, v29, v57
	v_add_f32_dpp v223, v214, v214 row_mirror row_mask:0xf bank_mask:0xf bound_ctrl:1
	v_fma_f32 v214, v22, v66, 0
	v_fmac_f32_e32 v214, v24, v68
	v_fmac_f32_e32 v214, v18, v62
	v_fmac_f32_e32 v214, v20, v64
	v_fmac_f32_e32 v214, v30, v58
	v_fmac_f32_e32 v214, v32, v60
	v_fmac_f32_e32 v214, v26, v54
	v_fmac_f32_e32 v214, v28, v56
	v_add_f32_e32 v214, v216, v214
	v_fma_f32 v216, v23, v51, 0
	v_fmac_f32_e32 v216, v25, v53
	v_add_f32_dpp v214, v214, v214 quad_perm:[1,0,3,2] row_mask:0xf bank_mask:0xf bound_ctrl:1
	v_fmac_f32_e32 v216, v19, v47
	v_fmac_f32_e32 v216, v21, v49
	v_add_f32_dpp v214, v214, v214 quad_perm:[2,3,0,1] row_mask:0xf bank_mask:0xf bound_ctrl:1
	v_fmac_f32_e32 v216, v31, v43
	v_fmac_f32_e32 v216, v33, v45
	v_add_f32_dpp v214, v214, v214 row_half_mirror row_mask:0xf bank_mask:0xf bound_ctrl:1
	v_fmac_f32_e32 v216, v27, v39
	v_fmac_f32_e32 v216, v29, v41
	v_add_f32_dpp v225, v214, v214 row_mirror row_mask:0xf bank_mask:0xf bound_ctrl:1
	v_fma_f32 v214, v22, v50, 0
	v_fmac_f32_e32 v214, v24, v52
	v_fmac_f32_e32 v214, v18, v46
	v_fmac_f32_e32 v214, v20, v48
	v_fmac_f32_e32 v214, v30, v42
	v_fmac_f32_e32 v214, v32, v44
	v_fmac_f32_e32 v214, v26, v38
	v_fmac_f32_e32 v214, v28, v40
	v_add_f32_e32 v214, v216, v214
	v_add_f32_dpp v213, v213, v213 quad_perm:[1,0,3,2] row_mask:0xf bank_mask:0xf bound_ctrl:1
	v_mov_b32_e32 v218, v215
	s_nop 1
	v_permlane16_swap_b32_e32 v218, v215
	v_add_f32_dpp v214, v214, v214 quad_perm:[1,0,3,2] row_mask:0xf bank_mask:0xf bound_ctrl:1
	v_add_f32_dpp v213, v213, v213 quad_perm:[2,3,0,1] row_mask:0xf bank_mask:0xf bound_ctrl:1
	v_mov_b32_e32 v220, v217
	s_nop 1
	v_permlane16_swap_b32_e32 v220, v217
	v_add_f32_dpp v214, v214, v214 quad_perm:[2,3,0,1] row_mask:0xf bank_mask:0xf bound_ctrl:1
	v_add_f32_dpp v213, v213, v213 row_half_mirror row_mask:0xf bank_mask:0xf bound_ctrl:1
	v_mov_b32_e32 v222, v219
	s_nop 1
	v_permlane16_swap_b32_e32 v222, v219
	v_add_f32_dpp v214, v214, v214 row_half_mirror row_mask:0xf bank_mask:0xf bound_ctrl:1
	v_add_f32_dpp v213, v213, v213 row_mirror row_mask:0xf bank_mask:0xf bound_ctrl:1
	v_mov_b32_e32 v216, v213
	s_nop 1
	v_permlane16_swap_b32_e32 v216, v213
	v_add_f32_dpp v227, v214, v214 row_mirror row_mask:0xf bank_mask:0xf bound_ctrl:1
	v_mov_b32_e32 v224, v221
	s_nop 1
	v_permlane16_swap_b32_e32 v224, v221
	v_mov_b32_e32 v226, v223
	s_nop 1
	v_permlane16_swap_b32_e32 v226, v223
	v_mov_b32_e32 v228, v225
	s_nop 1
	v_permlane16_swap_b32_e32 v228, v225
	v_mov_b32_e32 v229, v227
	s_nop 1
	v_permlane16_swap_b32_e32 v229, v227
	s_waitcnt lgkmcnt(0)
	v_add_f32_e32 v213, v213, v216
	v_add_f32_e32 v215, v215, v218
	v_add_f32_e32 v217, v217, v220
	v_add_f32_e32 v219, v219, v222
	s_waitcnt lgkmcnt(0)
	v_add_f32_e32 v221, v221, v224
	s_waitcnt lgkmcnt(0)
	v_add_f32_e32 v223, v223, v226
	s_waitcnt lgkmcnt(0)
	v_add_f32_e32 v225, v225, v228
	s_waitcnt lgkmcnt(0)
	v_add_f32_e32 v227, v227, v229
	v_mov_b32_e32 v214, v213
	s_nop 1
	v_permlane32_swap_b32_e32 v214, v213
	v_mov_b32_e32 v216, v215
	s_nop 1
	v_permlane32_swap_b32_e32 v216, v215
	v_mov_b32_e32 v218, v217
	s_nop 1
	v_permlane32_swap_b32_e32 v218, v217
	v_mov_b32_e32 v220, v219
	s_nop 1
	v_permlane32_swap_b32_e32 v220, v219
	v_mov_b32_e32 v222, v221
	s_nop 1
	v_permlane32_swap_b32_e32 v222, v221
	v_mov_b32_e32 v224, v223
	s_nop 1
	v_permlane32_swap_b32_e32 v224, v223
	v_mov_b32_e32 v226, v225
	s_nop 1
	v_permlane32_swap_b32_e32 v226, v225
	v_mov_b32_e32 v228, v227
	s_nop 1
	v_permlane32_swap_b32_e32 v228, v227
	s_and_saveexec_b64 s[22:23], s[2:3]
	s_cbranch_execz .LBB0_92
	s_waitcnt lgkmcnt(0)
	v_add_f32_e32 v227, v227, v228
	v_add_f32_e32 v225, v225, v226
	s_waitcnt vmcnt(8)
	v_add_f32_e32 v226, v37, v227
	v_mul_f32_e64 v227, |v226|, s30
	v_exp_f32_e32 v227, v227
	v_add_f32_e32 v221, v221, v222
	v_add_f32_e32 v222, v219, v220
	v_add_f32_e32 v213, v213, v214
	v_add_f32_e32 v219, 1.0, v227
	v_cmp_gt_f32_e32 vcc, s31, v219
	v_add_f32_e32 v227, v215, v216
	v_add_f32_e32 v216, v36, v225
	v_cndmask_b32_e64 v220, 0, 32, vcc
	v_ldexp_f32 v219, v219, v220
	v_log_f32_e32 v219, v219
	v_mul_f32_e64 v215, |v216|, s30
	v_exp_f32_e32 v215, v215
	v_add_f32_e32 v223, v223, v224
	v_mul_f32_e32 v214, 0x3f317217, v219
	v_fma_f32 v214, v219, s33, -v214
	v_fmac_f32_e32 v214, 0x3377d1cf, v219
	v_fmac_f32_e32 v214, 0x3f317217, v219
	v_cmp_lt_f32_e64 s[4:5], |v219|, s34
	v_add_f32_e32 v215, 1.0, v215
	v_add_f32_e32 v224, v217, v218
	v_cndmask_b32_e64 v214, v219, v214, s[4:5]
	v_cmp_gt_f32_e64 s[4:5], s31, v215
	v_add_f32_e32 v220, v35, v223
	v_mul_f32_e64 v219, |v220|, s30
	v_cndmask_b32_e64 v217, 0, 32, s[4:5]
	v_ldexp_f32 v215, v215, v217
	v_log_f32_e32 v218, v215
	v_cndmask_b32_e32 v215, 0, v212, vcc
	v_sub_f32_e32 v215, v214, v215
	v_exp_f32_e32 v219, v219
	v_mul_f32_e32 v214, 0x3f317217, v218
	v_fma_f32 v214, v218, s33, -v214
	v_fmac_f32_e32 v214, 0x3377d1cf, v218
	v_fmac_f32_e32 v214, 0x3f317217, v218
	v_cmp_lt_f32_e64 vcc, |v218|, s34
	v_add_f32_e32 v223, v34, v221
	v_mul_f32_e64 v221, |v223|, s30
	v_cndmask_b32_e32 v214, v218, v214, vcc
	v_add_f32_e32 v218, 1.0, v219
	v_cmp_gt_f32_e32 vcc, s31, v218
	v_exp_f32_e32 v221, v221
	v_mul_f32_e32 v213, 0xbfb8aa3b, v213
	v_cndmask_b32_e64 v219, 0, 32, vcc
	v_ldexp_f32 v218, v218, v219
	v_log_f32_e32 v218, v218
	v_cndmask_b32_e64 v219, 0, v212, s[4:5]
	v_sub_f32_e32 v214, v214, v219
	v_exp_f32_e32 v213, v213
	v_mul_f32_e32 v219, 0x3f317217, v218
	v_fma_f32 v219, v218, s33, -v219
	v_fmac_f32_e32 v219, 0x3377d1cf, v218
	v_fmac_f32_e32 v219, 0x3f317217, v218
	v_cmp_lt_f32_e64 s[4:5], |v218|, s34
	v_mul_f32_e32 v222, 0xbfb8aa3b, v222
	v_max_f32_e32 v217, 0, v226
	v_cndmask_b32_e64 v218, v218, v219, s[4:5]
	v_add_f32_e32 v219, 1.0, v221
	v_cmp_gt_f32_e64 s[4:5], s31, v219
	v_max_f32_e32 v216, 0, v216
	v_exp_f32_e32 v222, v222
	v_cndmask_b32_e64 v221, 0, 32, s[4:5]
	v_ldexp_f32 v219, v219, v221
	v_log_f32_e32 v225, v219
	v_cndmask_b32_e32 v219, 0, v212, vcc
	v_sub_f32_e32 v219, v218, v219
	v_max_f32_e32 v221, 0, v220
	v_mul_f32_e32 v218, 0x3f317217, v225
	v_fma_f32 v218, v225, s33, -v218
	v_fmac_f32_e32 v218, 0x3377d1cf, v225
	v_fmac_f32_e32 v218, 0x3f317217, v225
	v_cmp_lt_f32_e64 vcc, |v225|, s34
	v_cndmask_b32_e64 v220, 0, v212, s[4:5]
	v_pk_add_f32 v[214:215], v[216:217], v[214:215]
	v_cndmask_b32_e32 v218, v225, v218, vcc
	v_sub_f32_e32 v218, v218, v220
	v_max_f32_e32 v220, 0, v223
	v_mul_f32_e32 v223, 0xbfb8aa3b, v224
	v_mul_f32_e32 v224, 0xbfb8aa3b, v227
	v_exp_f32_e32 v224, v224
	v_exp_f32_e32 v223, v223
	v_pk_add_f32 v[218:219], v[220:221], v[218:219]
	v_add_f32_e32 v213, 1.0, v213
	v_pk_mul_f32 v[216:217], v[214:215], s[10:11]
	v_pk_mul_f32 v[214:215], v[218:219], s[8:9] neg_lo:[0,1] neg_hi:[0,1]
	v_rcp_f32_e32 v218, v213
	v_add_f32_e32 v213, 1.0, v224
	v_rcp_f32_e32 v219, v213
	v_add_f32_e32 v213, 1.0, v223
	v_rcp_f32_e32 v220, v213
	v_add_f32_e32 v213, 1.0, v222
	s_lshl_b64 s[4:5], s[20:21], 4
	v_rcp_f32_e32 v221, v213
	s_add_u32 s20, s24, s4
	s_addc_u32 s21, s25, s5
	s_add_u32 s4, s26, s4
	s_addc_u32 s5, s27, s5
	global_store_dwordx4 v201, v[218:221], s[20:21] sc1
	global_store_dwordx4 v201, v[214:217], s[4:5] sc1

.LBB0_95:
	s_waitcnt vmcnt(7) lgkmcnt(7)
	v_pk_mul_f32 v[214:215], v[172:173], v[172:173]
	s_waitcnt lgkmcnt(0)
	v_pk_mul_f32 v[216:217], v[170:171], v[170:171]
	s_waitcnt vmcnt(4)
	v_mul_f32_e32 v213, v178, v178
	s_waitcnt lgkmcnt(0)
	v_pk_mov_b32 v[218:219], v[216:217], v[214:215] op_sel:[1,0]
	v_mov_b32_e32 v217, v215
	v_pk_add_f32 v[214:215], v[218:219], v[216:217]
	v_pk_mul_f32 v[216:217], v[168:169], v[168:169]
	v_pk_mul_f32 v[218:219], v[166:167], v[166:167]
	v_pk_add_f32 v[214:215], v[214:215], v[214:215] op_sel:[0,1] op_sel_hi:[1,0]
	s_waitcnt lgkmcnt(0)
	v_pk_mov_b32 v[220:221], v[218:219], v[216:217] op_sel:[1,0]
	v_mov_b32_e32 v219, v217
	v_pk_add_f32 v[216:217], v[220:221], v[218:219]
	v_mul_f32_e32 v218, v179, v179
	v_pk_add_f32 v[216:217], v[216:217], v[216:217] op_sel:[0,1] op_sel_hi:[1,0]
	v_mov_b32_e32 v215, v213
	v_mov_b32_e32 v217, v218
	v_pk_add_f32 v[214:215], v[214:215], v[216:217]
	v_mul_f32_e32 v216, v187, v187
	v_mul_f32_e32 v219, v180, v180
	v_pk_fma_f32 v[216:217], v[186:187], v[186:187], v[216:217] op_sel_hi:[1,1,0]
	v_mul_f32_e32 v218, v189, v189
	v_mul_f32_e32 v220, v181, v181
	v_mov_b32_e32 v217, v219
	v_pk_fma_f32 v[218:219], v[188:189], v[188:189], v[218:219] op_sel_hi:[1,1,0]
	s_ashr_i32 s17, s16, 31
	v_mov_b32_e32 v219, v220
	v_pk_add_f32 v[216:217], v[216:217], v[218:219]
	s_lshl_b64 s[4:5], s[16:17], 11
	v_pk_add_f32 v[214:215], v[214:215], v[216:217]
	s_nop 0
	v_add_f32_e32 v213, v214, v215
	s_nop 1
	v_add_f32_dpp v213, v213, v213 quad_perm:[1,0,3,2] row_mask:0xf bank_mask:0xf bound_ctrl:1
	s_nop 1
	v_add_f32_dpp v213, v213, v213 quad_perm:[2,3,0,1] row_mask:0xf bank_mask:0xf bound_ctrl:1
	s_nop 1
	v_add_f32_dpp v213, v213, v213 row_half_mirror row_mask:0xf bank_mask:0xf bound_ctrl:1
	s_nop 1
	v_add_f32_dpp v213, v213, v213 row_mirror row_mask:0xf bank_mask:0xf bound_ctrl:1
	v_mov_b32_e32 v214, v213
	s_nop 1
	v_permlane16_swap_b32_e32 v214, v213
	s_waitcnt lgkmcnt(0)
	v_add_f32_e32 v213, v213, v214
	v_mov_b32_e32 v214, v213
	s_nop 1
	v_permlane32_swap_b32_e32 v214, v213
	s_waitcnt lgkmcnt(0)
	v_add_f32_e32 v213, v213, v214
	v_fmamk_f32 v213, v213, 0x3a800000, v211
	v_rsq_f32_e32 v230, v213
	ds_read_b128 v[214:217], v210
	ds_read_b128 v[218:221], v210 offset:4096
	ds_read_b128 v[222:225], v210 offset:1024
	ds_read_b128 v[226:229], v210 offset:5120
	v_pk_mul_f32 v[170:171], v[170:171], v[230:231] op_sel_hi:[1,0]
	v_pk_mul_f32 v[172:173], v[172:173], v[230:231] op_sel_hi:[1,0]
	s_waitcnt lgkmcnt(0)
	v_pk_fma_f32 v[170:171], v[214:215], v[170:171], v[218:219]
	v_pk_fma_f32 v[172:173], v[216:217], v[172:173], v[220:221]
	ds_read_b128 v[214:217], v210 offset:2048
	ds_read_b128 v[218:221], v210 offset:6144
	v_pk_mul_f32 v[166:167], v[166:167], v[230:231] op_sel_hi:[1,0]
	v_pk_mul_f32 v[168:169], v[168:169], v[230:231] op_sel_hi:[1,0]
	s_waitcnt lgkmcnt(0)
	v_pk_fma_f32 v[166:167], v[222:223], v[166:167], v[226:227]
	v_pk_fma_f32 v[168:169], v[224:225], v[168:169], v[228:229]
	ds_read_b128 v[222:225], v210 offset:3072
	ds_read_b128 v[226:229], v210 offset:7168
	v_pk_mul_f32 v[186:187], v[186:187], v[230:231] op_sel_hi:[1,0]
	v_pk_mul_f32 v[188:189], v[188:189], v[230:231] op_sel_hi:[1,0]
	s_waitcnt lgkmcnt(0)
	v_pk_fma_f32 v[186:187], v[214:215], v[186:187], v[218:219]
	v_pk_fma_f32 v[188:189], v[216:217], v[188:189], v[220:221]
	v_lshl_add_u64 v[214:215], v[206:207], 0, s[4:5]
	v_cvt_pk_bf16_f32 v216, v170, v171
	v_cvt_pk_bf16_f32 v217, v172, v173
	v_pk_mul_f32 v[178:179], v[178:179], v[230:231] op_sel_hi:[1,0]
	v_pk_mul_f32 v[180:181], v[180:181], v[230:231] op_sel_hi:[1,0]
	global_store_dwordx2 v[214:215], v[216:217], off
	v_cvt_pk_bf16_f32 v216, v166, v167
	v_cvt_pk_bf16_f32 v217, v168, v169
	s_waitcnt lgkmcnt(0)
	v_pk_fma_f32 v[180:181], v[224:225], v[180:181], v[228:229]
	v_pk_fma_f32 v[178:179], v[222:223], v[178:179], v[226:227]
	global_store_dwordx2 v[214:215], v[216:217], off offset:512
	v_cvt_pk_bf16_f32 v216, v186, v187
	v_cvt_pk_bf16_f32 v217, v188, v189
	global_store_dwordx2 v[214:215], v[216:217], off offset:1024
	v_cvt_pk_bf16_f32 v216, v178, v179
	v_cvt_pk_bf16_f32 v217, v180, v181
	global_store_dwordx2 v[214:215], v[216:217], off offset:1536
	v_fma_f32 v213, v170, v162, 0
	v_fma_f32 v214, v171, v163, 0
	v_fmac_f32_e32 v213, v172, v164
	v_fmac_f32_e32 v214, v173, v165
	v_fmac_f32_e32 v213, v166, v158
	v_fmac_f32_e32 v214, v167, v159
	v_fmac_f32_e32 v213, v168, v160
	v_fmac_f32_e32 v214, v169, v161
	v_fmac_f32_e32 v213, v186, v154
	v_fmac_f32_e32 v214, v187, v155
	v_fmac_f32_e32 v213, v188, v156
	v_fmac_f32_e32 v214, v189, v157
	v_fmac_f32_e32 v213, v178, v150
	v_fmac_f32_e32 v214, v179, v151
	v_fmac_f32_e32 v213, v180, v152
	v_fmac_f32_e32 v214, v181, v153
	v_add_f32_e32 v213, v213, v214
	v_fma_f32 v214, v170, v146, 0
	v_fma_f32 v215, v171, v147, 0
	v_fmac_f32_e32 v214, v172, v148
	v_fmac_f32_e32 v215, v173, v149
	v_fmac_f32_e32 v214, v166, v142
	v_fmac_f32_e32 v215, v167, v143
	v_fmac_f32_e32 v214, v168, v144
	v_fmac_f32_e32 v215, v169, v145
	v_fmac_f32_e32 v214, v186, v138
	v_fmac_f32_e32 v215, v187, v139
	v_fmac_f32_e32 v214, v188, v140
	v_fmac_f32_e32 v215, v189, v141
	v_fmac_f32_e32 v214, v178, v134
	v_fmac_f32_e32 v215, v179, v135
	v_fmac_f32_e32 v214, v180, v136
	v_fmac_f32_e32 v215, v181, v137
	v_add_f32_e32 v214, v214, v215
	v_fma_f32 v216, v171, v131, 0
	v_fmac_f32_e32 v216, v173, v133
	v_add_f32_dpp v214, v214, v214 quad_perm:[1,0,3,2] row_mask:0xf bank_mask:0xf bound_ctrl:1
	v_fmac_f32_e32 v216, v167, v127
	v_fmac_f32_e32 v216, v169, v129
	v_add_f32_dpp v214, v214, v214 quad_perm:[2,3,0,1] row_mask:0xf bank_mask:0xf bound_ctrl:1
	v_fmac_f32_e32 v216, v187, v123
	v_fmac_f32_e32 v216, v189, v125
	v_add_f32_dpp v214, v214, v214 row_half_mirror row_mask:0xf bank_mask:0xf bound_ctrl:1
	v_fmac_f32_e32 v216, v179, v119
	v_fmac_f32_e32 v216, v181, v121
	v_add_f32_dpp v215, v214, v214 row_mirror row_mask:0xf bank_mask:0xf bound_ctrl:1
	v_fma_f32 v214, v170, v130, 0
	v_fmac_f32_e32 v214, v172, v132
	v_fmac_f32_e32 v214, v166, v126
	v_fmac_f32_e32 v214, v168, v128
	v_fmac_f32_e32 v214, v186, v122
	v_fmac_f32_e32 v214, v188, v124
	v_fmac_f32_e32 v214, v178, v118
	v_fmac_f32_e32 v214, v180, v120
	v_add_f32_e32 v214, v214, v216
	v_fma_f32 v216, v171, v115, 0
	v_fmac_f32_e32 v216, v173, v117
	v_add_f32_dpp v214, v214, v214 quad_perm:[1,0,3,2] row_mask:0xf bank_mask:0xf bound_ctrl:1
	v_fmac_f32_e32 v216, v167, v111
	v_fmac_f32_e32 v216, v169, v113
	v_add_f32_dpp v214, v214, v214 quad_perm:[2,3,0,1] row_mask:0xf bank_mask:0xf bound_ctrl:1
	v_fmac_f32_e32 v216, v187, v107
	v_fmac_f32_e32 v216, v189, v109
	v_add_f32_dpp v214, v214, v214 row_half_mirror row_mask:0xf bank_mask:0xf bound_ctrl:1
	v_fmac_f32_e32 v216, v179, v103
	v_fmac_f32_e32 v216, v181, v105
	v_add_f32_dpp v217, v214, v214 row_mirror row_mask:0xf bank_mask:0xf bound_ctrl:1
	v_fma_f32 v214, v170, v114, 0
	v_fmac_f32_e32 v214, v172, v116
	v_fmac_f32_e32 v214, v166, v110
	v_fmac_f32_e32 v214, v168, v112
	v_fmac_f32_e32 v214, v186, v106
	v_fmac_f32_e32 v214, v188, v108
	v_fmac_f32_e32 v214, v178, v102
	v_fmac_f32_e32 v214, v180, v104
	v_add_f32_e32 v214, v214, v216
	v_fma_f32 v216, v171, v99, 0
	v_fmac_f32_e32 v216, v173, v101
	v_add_f32_dpp v214, v214, v214 quad_perm:[1,0,3,2] row_mask:0xf bank_mask:0xf bound_ctrl:1
	v_fmac_f32_e32 v216, v167, v95
	v_fmac_f32_e32 v216, v169, v97
	v_add_f32_dpp v214, v214, v214 quad_perm:[2,3,0,1] row_mask:0xf bank_mask:0xf bound_ctrl:1
	v_fmac_f32_e32 v216, v187, v91
	v_fmac_f32_e32 v216, v189, v93
	v_add_f32_dpp v214, v214, v214 row_half_mirror row_mask:0xf bank_mask:0xf bound_ctrl:1
	v_fmac_f32_e32 v216, v179, v87
	v_fmac_f32_e32 v216, v181, v89
	v_add_f32_dpp v219, v214, v214 row_mirror row_mask:0xf bank_mask:0xf bound_ctrl:1
	v_fma_f32 v214, v170, v98, 0
	v_fmac_f32_e32 v214, v172, v100
	v_fmac_f32_e32 v214, v166, v94
	v_fmac_f32_e32 v214, v168, v96
	v_fmac_f32_e32 v214, v186, v90
	v_fmac_f32_e32 v214, v188, v92
	v_fmac_f32_e32 v214, v178, v86
	v_fmac_f32_e32 v214, v180, v88
	v_add_f32_e32 v214, v214, v216
	v_fma_f32 v216, v171, v83, 0
	v_fmac_f32_e32 v216, v173, v85
	v_add_f32_dpp v214, v214, v214 quad_perm:[1,0,3,2] row_mask:0xf bank_mask:0xf bound_ctrl:1
	v_fmac_f32_e32 v216, v167, v79
	v_fmac_f32_e32 v216, v169, v81
	v_add_f32_dpp v214, v214, v214 quad_perm:[2,3,0,1] row_mask:0xf bank_mask:0xf bound_ctrl:1
	v_fmac_f32_e32 v216, v187, v75
	v_fmac_f32_e32 v216, v189, v77
	v_add_f32_dpp v214, v214, v214 row_half_mirror row_mask:0xf bank_mask:0xf bound_ctrl:1
	v_fmac_f32_e32 v216, v179, v71
	v_fmac_f32_e32 v216, v181, v73
	v_add_f32_dpp v221, v214, v214 row_mirror row_mask:0xf bank_mask:0xf bound_ctrl:1
	v_fma_f32 v214, v170, v82, 0
	v_fmac_f32_e32 v214, v172, v84
	v_fmac_f32_e32 v214, v166, v78
	v_fmac_f32_e32 v214, v168, v80
	v_fmac_f32_e32 v214, v186, v74
	v_fmac_f32_e32 v214, v188, v76
	v_fmac_f32_e32 v214, v178, v70
	v_fmac_f32_e32 v214, v180, v72
	v_add_f32_e32 v214, v214, v216
	v_fma_f32 v216, v171, v67, 0
	v_fmac_f32_e32 v216, v173, v69
	v_add_f32_dpp v214, v214, v214 quad_perm:[1,0,3,2] row_mask:0xf bank_mask:0xf bound_ctrl:1
	v_fmac_f32_e32 v216, v167, v63
	v_fmac_f32_e32 v216, v169, v65
	v_add_f32_dpp v214, v214, v214 quad_perm:[2,3,0,1] row_mask:0xf bank_mask:0xf bound_ctrl:1
	v_fmac_f32_e32 v216, v187, v59
	v_fmac_f32_e32 v216, v189, v61
	v_add_f32_dpp v214, v214, v214 row_half_mirror row_mask:0xf bank_mask:0xf bound_ctrl:1
	v_fmac_f32_e32 v216, v179, v55
	v_fmac_f32_e32 v216, v181, v57
	v_add_f32_dpp v223, v214, v214 row_mirror row_mask:0xf bank_mask:0xf bound_ctrl:1
	v_fma_f32 v214, v170, v66, 0
	v_fmac_f32_e32 v214, v172, v68
	v_fmac_f32_e32 v214, v166, v62
	v_fmac_f32_e32 v214, v168, v64
	v_fmac_f32_e32 v214, v186, v58
	v_fmac_f32_e32 v214, v188, v60
	v_fmac_f32_e32 v214, v178, v54
	v_fmac_f32_e32 v214, v180, v56
	v_add_f32_e32 v214, v214, v216
	v_fma_f32 v216, v171, v51, 0
	v_fmac_f32_e32 v216, v173, v53
	v_add_f32_dpp v214, v214, v214 quad_perm:[1,0,3,2] row_mask:0xf bank_mask:0xf bound_ctrl:1
	v_fmac_f32_e32 v216, v167, v47
	v_fmac_f32_e32 v216, v169, v49
	v_add_f32_dpp v214, v214, v214 quad_perm:[2,3,0,1] row_mask:0xf bank_mask:0xf bound_ctrl:1
	v_fmac_f32_e32 v216, v187, v43
	v_fmac_f32_e32 v216, v189, v45
	v_add_f32_dpp v214, v214, v214 row_half_mirror row_mask:0xf bank_mask:0xf bound_ctrl:1
	v_fmac_f32_e32 v216, v179, v39
	v_fmac_f32_e32 v216, v181, v41
	v_add_f32_dpp v225, v214, v214 row_mirror row_mask:0xf bank_mask:0xf bound_ctrl:1
	v_fma_f32 v214, v170, v50, 0
	v_fmac_f32_e32 v214, v172, v52
	v_fmac_f32_e32 v214, v166, v46
	v_fmac_f32_e32 v214, v168, v48
	v_fmac_f32_e32 v214, v186, v42
	v_fmac_f32_e32 v214, v188, v44
	v_fmac_f32_e32 v214, v178, v38
	v_fmac_f32_e32 v214, v180, v40
	v_add_f32_e32 v214, v214, v216
	v_add_f32_dpp v213, v213, v213 quad_perm:[1,0,3,2] row_mask:0xf bank_mask:0xf bound_ctrl:1
	v_mov_b32_e32 v218, v215
	s_nop 1
	v_permlane16_swap_b32_e32 v218, v215
	v_add_f32_dpp v214, v214, v214 quad_perm:[1,0,3,2] row_mask:0xf bank_mask:0xf bound_ctrl:1
	v_add_f32_dpp v213, v213, v213 quad_perm:[2,3,0,1] row_mask:0xf bank_mask:0xf bound_ctrl:1
	v_mov_b32_e32 v220, v217
	s_nop 1
	v_permlane16_swap_b32_e32 v220, v217
	v_add_f32_dpp v214, v214, v214 quad_perm:[2,3,0,1] row_mask:0xf bank_mask:0xf bound_ctrl:1
	v_add_f32_dpp v213, v213, v213 row_half_mirror row_mask:0xf bank_mask:0xf bound_ctrl:1
	v_mov_b32_e32 v222, v219
	s_nop 1
	v_permlane16_swap_b32_e32 v222, v219
	v_add_f32_dpp v214, v214, v214 row_half_mirror row_mask:0xf bank_mask:0xf bound_ctrl:1
	v_add_f32_dpp v213, v213, v213 row_mirror row_mask:0xf bank_mask:0xf bound_ctrl:1
	v_mov_b32_e32 v216, v213
	s_nop 1
	v_permlane16_swap_b32_e32 v216, v213
	v_add_f32_dpp v227, v214, v214 row_mirror row_mask:0xf bank_mask:0xf bound_ctrl:1
	v_mov_b32_e32 v224, v221
	s_nop 1
	v_permlane16_swap_b32_e32 v224, v221
	v_mov_b32_e32 v226, v223
	s_nop 1
	v_permlane16_swap_b32_e32 v226, v223
	v_mov_b32_e32 v228, v225
	s_nop 1
	v_permlane16_swap_b32_e32 v228, v225
	v_mov_b32_e32 v229, v227
	s_nop 1
	v_permlane16_swap_b32_e32 v229, v227
	s_waitcnt lgkmcnt(0)
	v_add_f32_e32 v213, v213, v216
	v_add_f32_e32 v215, v215, v218
	v_add_f32_e32 v217, v217, v220
	v_add_f32_e32 v219, v219, v222
	s_waitcnt lgkmcnt(0)
	v_add_f32_e32 v221, v221, v224
	s_waitcnt lgkmcnt(0)
	v_add_f32_e32 v223, v223, v226
	s_waitcnt lgkmcnt(0)
	v_add_f32_e32 v225, v225, v228
	s_waitcnt lgkmcnt(0)
	v_add_f32_e32 v227, v227, v229
	v_mov_b32_e32 v214, v213
	s_nop 1
	v_permlane32_swap_b32_e32 v214, v213
	v_mov_b32_e32 v216, v215
	s_nop 1
	v_permlane32_swap_b32_e32 v216, v215
	v_mov_b32_e32 v218, v217
	s_nop 1
	v_permlane32_swap_b32_e32 v218, v217
	v_mov_b32_e32 v220, v219
	s_nop 1
	v_permlane32_swap_b32_e32 v220, v219
	v_mov_b32_e32 v222, v221
	s_nop 1
	v_permlane32_swap_b32_e32 v222, v221
	v_mov_b32_e32 v224, v223
	s_nop 1
	v_permlane32_swap_b32_e32 v224, v223
	v_mov_b32_e32 v226, v225
	s_nop 1
	v_permlane32_swap_b32_e32 v226, v225
	v_mov_b32_e32 v228, v227
	s_nop 1
	v_permlane32_swap_b32_e32 v228, v227
	s_and_saveexec_b64 s[18:19], s[2:3]
	s_cbranch_execz .LBB0_97
	s_waitcnt lgkmcnt(0)
	v_add_f32_e32 v227, v227, v228
	v_add_f32_e32 v225, v225, v226
	v_add_f32_e32 v226, v37, v227
	v_mul_f32_e64 v227, |v226|, s30
	v_exp_f32_e32 v227, v227
	v_add_f32_e32 v221, v221, v222
	v_add_f32_e32 v222, v219, v220
	v_add_f32_e32 v213, v213, v214
	v_add_f32_e32 v219, 1.0, v227
	v_cmp_gt_f32_e32 vcc, s31, v219
	v_add_f32_e32 v227, v215, v216
	v_add_f32_e32 v216, v36, v225
	v_cndmask_b32_e64 v220, 0, 32, vcc
	v_ldexp_f32 v219, v219, v220
	v_log_f32_e32 v219, v219
	v_mul_f32_e64 v215, |v216|, s30
	v_exp_f32_e32 v215, v215
	v_add_f32_e32 v223, v223, v224
	v_mul_f32_e32 v214, 0x3f317217, v219
	v_fma_f32 v214, v219, s33, -v214
	v_fmac_f32_e32 v214, 0x3377d1cf, v219
	v_fmac_f32_e32 v214, 0x3f317217, v219
	v_cmp_lt_f32_e64 s[4:5], |v219|, s34
	v_add_f32_e32 v215, 1.0, v215
	v_add_f32_e32 v224, v217, v218
	v_cndmask_b32_e64 v214, v219, v214, s[4:5]
	v_cmp_gt_f32_e64 s[4:5], s31, v215
	v_add_f32_e32 v220, v35, v223
	v_mul_f32_e64 v219, |v220|, s30
	v_cndmask_b32_e64 v217, 0, 32, s[4:5]
	v_ldexp_f32 v215, v215, v217
	v_log_f32_e32 v218, v215
	v_cndmask_b32_e32 v215, 0, v212, vcc
	v_sub_f32_e32 v215, v214, v215
	v_exp_f32_e32 v219, v219
	v_mul_f32_e32 v214, 0x3f317217, v218
	v_fma_f32 v214, v218, s33, -v214
	v_fmac_f32_e32 v214, 0x3377d1cf, v218
	v_fmac_f32_e32 v214, 0x3f317217, v218
	v_cmp_lt_f32_e64 vcc, |v218|, s34
	v_add_f32_e32 v223, v34, v221
	v_mul_f32_e64 v221, |v223|, s30
	v_cndmask_b32_e32 v214, v218, v214, vcc
	v_add_f32_e32 v218, 1.0, v219
	v_cmp_gt_f32_e32 vcc, s31, v218
	v_exp_f32_e32 v221, v221
	v_mul_f32_e32 v213, 0xbfb8aa3b, v213
	v_cndmask_b32_e64 v219, 0, 32, vcc
	v_ldexp_f32 v218, v218, v219
	v_log_f32_e32 v218, v218
	v_cndmask_b32_e64 v219, 0, v212, s[4:5]
	v_sub_f32_e32 v214, v214, v219
	v_exp_f32_e32 v213, v213
	v_mul_f32_e32 v219, 0x3f317217, v218
	v_fma_f32 v219, v218, s33, -v219
	v_fmac_f32_e32 v219, 0x3377d1cf, v218
	v_fmac_f32_e32 v219, 0x3f317217, v218
	v_cmp_lt_f32_e64 s[4:5], |v218|, s34
	v_mul_f32_e32 v222, 0xbfb8aa3b, v222
	v_max_f32_e32 v217, 0, v226
	v_cndmask_b32_e64 v218, v218, v219, s[4:5]
	v_add_f32_e32 v219, 1.0, v221
	v_cmp_gt_f32_e64 s[4:5], s31, v219
	v_max_f32_e32 v216, 0, v216
	v_exp_f32_e32 v222, v222
	v_cndmask_b32_e64 v221, 0, 32, s[4:5]
	v_ldexp_f32 v219, v219, v221
	v_log_f32_e32 v225, v219
	v_cndmask_b32_e32 v219, 0, v212, vcc
	v_sub_f32_e32 v219, v218, v219
	v_max_f32_e32 v221, 0, v220
	v_mul_f32_e32 v218, 0x3f317217, v225
	v_fma_f32 v218, v225, s33, -v218
	v_fmac_f32_e32 v218, 0x3377d1cf, v225
	v_fmac_f32_e32 v218, 0x3f317217, v225
	v_cmp_lt_f32_e64 vcc, |v225|, s34
	v_cndmask_b32_e64 v220, 0, v212, s[4:5]
	v_pk_add_f32 v[214:215], v[216:217], v[214:215]
	v_cndmask_b32_e32 v218, v225, v218, vcc
	v_sub_f32_e32 v218, v218, v220
	v_max_f32_e32 v220, 0, v223
	v_mul_f32_e32 v223, 0xbfb8aa3b, v224
	v_mul_f32_e32 v224, 0xbfb8aa3b, v227
	v_exp_f32_e32 v224, v224
	v_exp_f32_e32 v223, v223
	v_pk_add_f32 v[218:219], v[220:221], v[218:219]
	v_add_f32_e32 v213, 1.0, v213
	v_pk_mul_f32 v[216:217], v[214:215], s[10:11]
	v_pk_mul_f32 v[214:215], v[218:219], s[8:9] neg_lo:[0,1] neg_hi:[0,1]
	v_rcp_f32_e32 v218, v213
	v_add_f32_e32 v213, 1.0, v224
	v_rcp_f32_e32 v219, v213
	v_add_f32_e32 v213, 1.0, v223
	v_rcp_f32_e32 v220, v213
	v_add_f32_e32 v213, 1.0, v222
	s_lshl_b64 s[4:5], s[16:17], 4
	v_rcp_f32_e32 v221, v213
	s_add_u32 s16, s24, s4
	s_addc_u32 s17, s25, s5
	s_add_u32 s4, s26, s4
	s_addc_u32 s5, s27, s5
	global_store_dwordx4 v201, v[218:221], s[16:17] sc1
	global_store_dwordx4 v201, v[214:217], s[4:5] sc1

.LBB0_98:
	s_waitcnt vmcnt(7) lgkmcnt(7)
	v_pk_mul_f32 v[214:215], v[184:185], v[184:185]
	s_waitcnt lgkmcnt(0)
	v_pk_mul_f32 v[216:217], v[182:183], v[182:183]
	s_waitcnt vmcnt(4)
	v_mul_f32_e32 v213, v190, v190
	s_waitcnt lgkmcnt(0)
	v_pk_mov_b32 v[218:219], v[216:217], v[214:215] op_sel:[1,0]
	v_mov_b32_e32 v217, v215
	v_pk_add_f32 v[214:215], v[218:219], v[216:217]
	v_pk_mul_f32 v[216:217], v[176:177], v[176:177]
	v_pk_mul_f32 v[218:219], v[174:175], v[174:175]
	v_pk_add_f32 v[214:215], v[214:215], v[214:215] op_sel:[0,1] op_sel_hi:[1,0]
	s_waitcnt lgkmcnt(0)
	v_pk_mov_b32 v[220:221], v[218:219], v[216:217] op_sel:[1,0]
	v_mov_b32_e32 v219, v217
	v_pk_add_f32 v[216:217], v[220:221], v[218:219]
	v_mul_f32_e32 v218, v191, v191
	v_pk_add_f32 v[216:217], v[216:217], v[216:217] op_sel:[0,1] op_sel_hi:[1,0]
	v_mov_b32_e32 v215, v213
	v_mov_b32_e32 v217, v218
	v_pk_add_f32 v[214:215], v[214:215], v[216:217]
	v_mul_f32_e32 v216, v195, v195
	v_mul_f32_e32 v219, v192, v192
	v_pk_fma_f32 v[216:217], v[194:195], v[194:195], v[216:217] op_sel_hi:[1,1,0]
	v_mul_f32_e32 v218, v197, v197
	v_mul_f32_e32 v220, v193, v193
	v_mov_b32_e32 v217, v219
	v_pk_fma_f32 v[218:219], v[196:197], v[196:197], v[218:219] op_sel_hi:[1,1,0]
	s_ashr_i32 s13, s12, 31
	v_mov_b32_e32 v219, v220
	v_pk_add_f32 v[216:217], v[216:217], v[218:219]
	s_lshl_b64 s[4:5], s[12:13], 11
	v_pk_add_f32 v[214:215], v[214:215], v[216:217]
	s_nop 0
	v_add_f32_e32 v213, v214, v215
	s_nop 1
	v_add_f32_dpp v213, v213, v213 quad_perm:[1,0,3,2] row_mask:0xf bank_mask:0xf bound_ctrl:1
	s_nop 1
	v_add_f32_dpp v213, v213, v213 quad_perm:[2,3,0,1] row_mask:0xf bank_mask:0xf bound_ctrl:1
	s_nop 1
	v_add_f32_dpp v213, v213, v213 row_half_mirror row_mask:0xf bank_mask:0xf bound_ctrl:1
	s_nop 1
	v_add_f32_dpp v213, v213, v213 row_mirror row_mask:0xf bank_mask:0xf bound_ctrl:1
	v_mov_b32_e32 v214, v213
	s_nop 1
	v_permlane16_swap_b32_e32 v214, v213
	s_waitcnt lgkmcnt(0)
	v_add_f32_e32 v213, v213, v214
	v_mov_b32_e32 v214, v213
	s_nop 1
	v_permlane32_swap_b32_e32 v214, v213
	s_waitcnt lgkmcnt(0)
	v_add_f32_e32 v213, v213, v214
	v_fmamk_f32 v213, v213, 0x3a800000, v211
	v_rsq_f32_e32 v230, v213
	ds_read_b128 v[214:217], v210
	ds_read_b128 v[218:221], v210 offset:4096
	ds_read_b128 v[222:225], v210 offset:1024
	ds_read_b128 v[226:229], v210 offset:5120
	v_pk_mul_f32 v[182:183], v[182:183], v[230:231] op_sel_hi:[1,0]
	v_pk_mul_f32 v[184:185], v[184:185], v[230:231] op_sel_hi:[1,0]
	s_waitcnt lgkmcnt(0)
	v_pk_fma_f32 v[182:183], v[214:215], v[182:183], v[218:219]
	v_pk_fma_f32 v[184:185], v[216:217], v[184:185], v[220:221]
	ds_read_b128 v[214:217], v210 offset:2048
	ds_read_b128 v[218:221], v210 offset:6144
	v_pk_mul_f32 v[174:175], v[174:175], v[230:231] op_sel_hi:[1,0]
	v_pk_mul_f32 v[176:177], v[176:177], v[230:231] op_sel_hi:[1,0]
	s_waitcnt lgkmcnt(0)
	v_pk_fma_f32 v[174:175], v[222:223], v[174:175], v[226:227]
	v_pk_fma_f32 v[176:177], v[224:225], v[176:177], v[228:229]
	ds_read_b128 v[222:225], v210 offset:3072
	ds_read_b128 v[226:229], v210 offset:7168
	v_pk_mul_f32 v[194:195], v[194:195], v[230:231] op_sel_hi:[1,0]
	v_pk_mul_f32 v[196:197], v[196:197], v[230:231] op_sel_hi:[1,0]
	s_waitcnt lgkmcnt(0)
	v_pk_fma_f32 v[194:195], v[214:215], v[194:195], v[218:219]
	v_pk_fma_f32 v[196:197], v[216:217], v[196:197], v[220:221]
	v_lshl_add_u64 v[214:215], v[206:207], 0, s[4:5]
	v_cvt_pk_bf16_f32 v216, v182, v183
	v_cvt_pk_bf16_f32 v217, v184, v185
	v_pk_mul_f32 v[190:191], v[190:191], v[230:231] op_sel_hi:[1,0]
	v_pk_mul_f32 v[192:193], v[192:193], v[230:231] op_sel_hi:[1,0]
	global_store_dwordx2 v[214:215], v[216:217], off
	v_cvt_pk_bf16_f32 v216, v174, v175
	v_cvt_pk_bf16_f32 v217, v176, v177
	s_waitcnt lgkmcnt(0)
	v_pk_fma_f32 v[192:193], v[224:225], v[192:193], v[228:229]
	v_pk_fma_f32 v[190:191], v[222:223], v[190:191], v[226:227]
	global_store_dwordx2 v[214:215], v[216:217], off offset:512
	v_cvt_pk_bf16_f32 v216, v194, v195
	v_cvt_pk_bf16_f32 v217, v196, v197
	global_store_dwordx2 v[214:215], v[216:217], off offset:1024
	v_cvt_pk_bf16_f32 v216, v190, v191
	v_cvt_pk_bf16_f32 v217, v192, v193
	global_store_dwordx2 v[214:215], v[216:217], off offset:1536
	v_fma_f32 v213, v182, v162, 0
	v_fma_f32 v214, v183, v163, 0
	v_fmac_f32_e32 v213, v184, v164
	v_fmac_f32_e32 v214, v185, v165
	v_fmac_f32_e32 v213, v174, v158
	v_fmac_f32_e32 v214, v175, v159
	v_fmac_f32_e32 v213, v176, v160
	v_fmac_f32_e32 v214, v177, v161
	v_fmac_f32_e32 v213, v194, v154
	v_fmac_f32_e32 v214, v195, v155
	v_fmac_f32_e32 v213, v196, v156
	v_fmac_f32_e32 v214, v197, v157
	v_fmac_f32_e32 v213, v190, v150
	v_fmac_f32_e32 v214, v191, v151
	v_fmac_f32_e32 v213, v192, v152
	v_fmac_f32_e32 v214, v193, v153
	v_add_f32_e32 v213, v213, v214
	v_fma_f32 v214, v182, v146, 0
	v_fma_f32 v215, v183, v147, 0
	v_fmac_f32_e32 v214, v184, v148
	v_fmac_f32_e32 v215, v185, v149
	v_fmac_f32_e32 v214, v174, v142
	v_fmac_f32_e32 v215, v175, v143
	v_fmac_f32_e32 v214, v176, v144
	v_fmac_f32_e32 v215, v177, v145
	v_fmac_f32_e32 v214, v194, v138
	v_fmac_f32_e32 v215, v195, v139
	v_fmac_f32_e32 v214, v196, v140
	v_fmac_f32_e32 v215, v197, v141
	v_fmac_f32_e32 v214, v190, v134
	v_fmac_f32_e32 v215, v191, v135
	v_fmac_f32_e32 v214, v192, v136
	v_fmac_f32_e32 v215, v193, v137
	v_add_f32_e32 v214, v214, v215
	v_fma_f32 v216, v183, v131, 0
	v_fmac_f32_e32 v216, v185, v133
	v_add_f32_dpp v214, v214, v214 quad_perm:[1,0,3,2] row_mask:0xf bank_mask:0xf bound_ctrl:1
	v_fmac_f32_e32 v216, v175, v127
	v_fmac_f32_e32 v216, v177, v129
	v_add_f32_dpp v214, v214, v214 quad_perm:[2,3,0,1] row_mask:0xf bank_mask:0xf bound_ctrl:1
	v_fmac_f32_e32 v216, v195, v123
	v_fmac_f32_e32 v216, v197, v125
	v_add_f32_dpp v214, v214, v214 row_half_mirror row_mask:0xf bank_mask:0xf bound_ctrl:1
	v_fmac_f32_e32 v216, v191, v119
	v_fmac_f32_e32 v216, v193, v121
	v_add_f32_dpp v215, v214, v214 row_mirror row_mask:0xf bank_mask:0xf bound_ctrl:1
	v_fma_f32 v214, v182, v130, 0
	v_fmac_f32_e32 v214, v184, v132
	v_fmac_f32_e32 v214, v174, v126
	v_fmac_f32_e32 v214, v176, v128
	v_fmac_f32_e32 v214, v194, v122
	v_fmac_f32_e32 v214, v196, v124
	v_fmac_f32_e32 v214, v190, v118
	v_fmac_f32_e32 v214, v192, v120
	v_add_f32_e32 v214, v214, v216
	v_fma_f32 v216, v183, v115, 0
	v_fmac_f32_e32 v216, v185, v117
	v_add_f32_dpp v214, v214, v214 quad_perm:[1,0,3,2] row_mask:0xf bank_mask:0xf bound_ctrl:1
	v_fmac_f32_e32 v216, v175, v111
	v_fmac_f32_e32 v216, v177, v113
	v_add_f32_dpp v214, v214, v214 quad_perm:[2,3,0,1] row_mask:0xf bank_mask:0xf bound_ctrl:1
	v_fmac_f32_e32 v216, v195, v107
	v_fmac_f32_e32 v216, v197, v109
	v_add_f32_dpp v214, v214, v214 row_half_mirror row_mask:0xf bank_mask:0xf bound_ctrl:1
	v_fmac_f32_e32 v216, v191, v103
	v_fmac_f32_e32 v216, v193, v105
	v_add_f32_dpp v217, v214, v214 row_mirror row_mask:0xf bank_mask:0xf bound_ctrl:1
	v_fma_f32 v214, v182, v114, 0
	v_fmac_f32_e32 v214, v184, v116
	v_fmac_f32_e32 v214, v174, v110
	v_fmac_f32_e32 v214, v176, v112
	v_fmac_f32_e32 v214, v194, v106
	v_fmac_f32_e32 v214, v196, v108
	v_fmac_f32_e32 v214, v190, v102
	v_fmac_f32_e32 v214, v192, v104
	v_add_f32_e32 v214, v214, v216
	v_fma_f32 v216, v183, v99, 0
	v_fmac_f32_e32 v216, v185, v101
	v_add_f32_dpp v214, v214, v214 quad_perm:[1,0,3,2] row_mask:0xf bank_mask:0xf bound_ctrl:1
	v_fmac_f32_e32 v216, v175, v95
	v_fmac_f32_e32 v216, v177, v97
	v_add_f32_dpp v214, v214, v214 quad_perm:[2,3,0,1] row_mask:0xf bank_mask:0xf bound_ctrl:1
	v_fmac_f32_e32 v216, v195, v91
	v_fmac_f32_e32 v216, v197, v93
	v_add_f32_dpp v214, v214, v214 row_half_mirror row_mask:0xf bank_mask:0xf bound_ctrl:1
	v_fmac_f32_e32 v216, v191, v87
	v_fmac_f32_e32 v216, v193, v89
	v_add_f32_dpp v219, v214, v214 row_mirror row_mask:0xf bank_mask:0xf bound_ctrl:1
	v_fma_f32 v214, v182, v98, 0
	v_fmac_f32_e32 v214, v184, v100
	v_fmac_f32_e32 v214, v174, v94
	v_fmac_f32_e32 v214, v176, v96
	v_fmac_f32_e32 v214, v194, v90
	v_fmac_f32_e32 v214, v196, v92
	v_fmac_f32_e32 v214, v190, v86
	v_fmac_f32_e32 v214, v192, v88
	v_add_f32_e32 v214, v214, v216
	v_fma_f32 v216, v183, v83, 0
	v_fmac_f32_e32 v216, v185, v85
	v_add_f32_dpp v214, v214, v214 quad_perm:[1,0,3,2] row_mask:0xf bank_mask:0xf bound_ctrl:1
	v_fmac_f32_e32 v216, v175, v79
	v_fmac_f32_e32 v216, v177, v81
	v_add_f32_dpp v214, v214, v214 quad_perm:[2,3,0,1] row_mask:0xf bank_mask:0xf bound_ctrl:1
	v_fmac_f32_e32 v216, v195, v75
	v_fmac_f32_e32 v216, v197, v77
	v_add_f32_dpp v214, v214, v214 row_half_mirror row_mask:0xf bank_mask:0xf bound_ctrl:1
	v_fmac_f32_e32 v216, v191, v71
	v_fmac_f32_e32 v216, v193, v73
	v_add_f32_dpp v221, v214, v214 row_mirror row_mask:0xf bank_mask:0xf bound_ctrl:1
	v_fma_f32 v214, v182, v82, 0
	v_fmac_f32_e32 v214, v184, v84
	v_fmac_f32_e32 v214, v174, v78
	v_fmac_f32_e32 v214, v176, v80
	v_fmac_f32_e32 v214, v194, v74
	v_fmac_f32_e32 v214, v196, v76
	v_fmac_f32_e32 v214, v190, v70
	v_fmac_f32_e32 v214, v192, v72
	v_add_f32_e32 v214, v214, v216
	v_fma_f32 v216, v183, v67, 0
	v_fmac_f32_e32 v216, v185, v69
	v_add_f32_dpp v214, v214, v214 quad_perm:[1,0,3,2] row_mask:0xf bank_mask:0xf bound_ctrl:1
	v_fmac_f32_e32 v216, v175, v63
	v_fmac_f32_e32 v216, v177, v65
	v_add_f32_dpp v214, v214, v214 quad_perm:[2,3,0,1] row_mask:0xf bank_mask:0xf bound_ctrl:1
	v_fmac_f32_e32 v216, v195, v59
	v_fmac_f32_e32 v216, v197, v61
	v_add_f32_dpp v214, v214, v214 row_half_mirror row_mask:0xf bank_mask:0xf bound_ctrl:1
	v_fmac_f32_e32 v216, v191, v55
	v_fmac_f32_e32 v216, v193, v57
	v_add_f32_dpp v223, v214, v214 row_mirror row_mask:0xf bank_mask:0xf bound_ctrl:1
	v_fma_f32 v214, v182, v66, 0
	v_fmac_f32_e32 v214, v184, v68
	v_fmac_f32_e32 v214, v174, v62
	v_fmac_f32_e32 v214, v176, v64
	v_fmac_f32_e32 v214, v194, v58
	v_fmac_f32_e32 v214, v196, v60
	v_fmac_f32_e32 v214, v190, v54
	v_fmac_f32_e32 v214, v192, v56
	v_add_f32_e32 v214, v214, v216
	v_fma_f32 v216, v183, v51, 0
	v_fmac_f32_e32 v216, v185, v53
	v_add_f32_dpp v214, v214, v214 quad_perm:[1,0,3,2] row_mask:0xf bank_mask:0xf bound_ctrl:1
	v_fmac_f32_e32 v216, v175, v47
	v_fmac_f32_e32 v216, v177, v49
	v_add_f32_dpp v214, v214, v214 quad_perm:[2,3,0,1] row_mask:0xf bank_mask:0xf bound_ctrl:1
	v_fmac_f32_e32 v216, v195, v43
	v_fmac_f32_e32 v216, v197, v45
	v_add_f32_dpp v214, v214, v214 row_half_mirror row_mask:0xf bank_mask:0xf bound_ctrl:1
	v_fmac_f32_e32 v216, v191, v39
	v_fmac_f32_e32 v216, v193, v41
	v_add_f32_dpp v225, v214, v214 row_mirror row_mask:0xf bank_mask:0xf bound_ctrl:1
	v_fma_f32 v214, v182, v50, 0
	v_fmac_f32_e32 v214, v184, v52
	v_fmac_f32_e32 v214, v174, v46
	v_fmac_f32_e32 v214, v176, v48
	v_fmac_f32_e32 v214, v194, v42
	v_fmac_f32_e32 v214, v196, v44
	v_fmac_f32_e32 v214, v190, v38
	v_fmac_f32_e32 v214, v192, v40
	v_add_f32_e32 v214, v214, v216
	v_add_f32_dpp v213, v213, v213 quad_perm:[1,0,3,2] row_mask:0xf bank_mask:0xf bound_ctrl:1
	v_mov_b32_e32 v218, v215
	s_nop 1
	v_permlane16_swap_b32_e32 v218, v215
	v_add_f32_dpp v214, v214, v214 quad_perm:[1,0,3,2] row_mask:0xf bank_mask:0xf bound_ctrl:1
	v_add_f32_dpp v213, v213, v213 quad_perm:[2,3,0,1] row_mask:0xf bank_mask:0xf bound_ctrl:1
	v_mov_b32_e32 v220, v217
	s_nop 1
	v_permlane16_swap_b32_e32 v220, v217
	v_add_f32_dpp v214, v214, v214 quad_perm:[2,3,0,1] row_mask:0xf bank_mask:0xf bound_ctrl:1
	v_add_f32_dpp v213, v213, v213 row_half_mirror row_mask:0xf bank_mask:0xf bound_ctrl:1
	v_mov_b32_e32 v222, v219
	s_nop 1
	v_permlane16_swap_b32_e32 v222, v219
	v_add_f32_dpp v214, v214, v214 row_half_mirror row_mask:0xf bank_mask:0xf bound_ctrl:1
	v_add_f32_dpp v213, v213, v213 row_mirror row_mask:0xf bank_mask:0xf bound_ctrl:1
	v_mov_b32_e32 v216, v213
	s_nop 1
	v_permlane16_swap_b32_e32 v216, v213
	v_add_f32_dpp v227, v214, v214 row_mirror row_mask:0xf bank_mask:0xf bound_ctrl:1
	v_mov_b32_e32 v224, v221
	s_nop 1
	v_permlane16_swap_b32_e32 v224, v221
	v_mov_b32_e32 v226, v223
	s_nop 1
	v_permlane16_swap_b32_e32 v226, v223
	v_mov_b32_e32 v228, v225
	s_nop 1
	v_permlane16_swap_b32_e32 v228, v225
	v_mov_b32_e32 v229, v227
	s_nop 1
	v_permlane16_swap_b32_e32 v229, v227
	s_waitcnt lgkmcnt(0)
	v_add_f32_e32 v213, v213, v216
	v_add_f32_e32 v215, v215, v218
	v_add_f32_e32 v217, v217, v220
	v_add_f32_e32 v219, v219, v222
	s_waitcnt lgkmcnt(0)
	v_add_f32_e32 v221, v221, v224
	s_waitcnt lgkmcnt(0)
	v_add_f32_e32 v223, v223, v226
	s_waitcnt lgkmcnt(0)
	v_add_f32_e32 v225, v225, v228
	s_waitcnt lgkmcnt(0)
	v_add_f32_e32 v227, v227, v229
	v_mov_b32_e32 v214, v213
	s_nop 1
	v_permlane32_swap_b32_e32 v214, v213
	v_mov_b32_e32 v216, v215
	s_nop 1
	v_permlane32_swap_b32_e32 v216, v215
	v_mov_b32_e32 v218, v217
	s_nop 1
	v_permlane32_swap_b32_e32 v218, v217
	v_mov_b32_e32 v220, v219
	s_nop 1
	v_permlane32_swap_b32_e32 v220, v219
	v_mov_b32_e32 v222, v221
	s_nop 1
	v_permlane32_swap_b32_e32 v222, v221
	v_mov_b32_e32 v224, v223
	s_nop 1
	v_permlane32_swap_b32_e32 v224, v223
	v_mov_b32_e32 v226, v225
	s_nop 1
	v_permlane32_swap_b32_e32 v226, v225
	v_mov_b32_e32 v228, v227
	s_nop 1
	v_permlane32_swap_b32_e32 v228, v227
	s_and_saveexec_b64 s[14:15], s[2:3]
	s_cbranch_execz .LBB0_77
	s_waitcnt lgkmcnt(0)
	v_add_f32_e32 v227, v227, v228
	v_add_f32_e32 v225, v225, v226
	v_add_f32_e32 v226, v37, v227
	v_mul_f32_e64 v227, |v226|, s30
	v_exp_f32_e32 v227, v227
	v_add_f32_e32 v221, v221, v222
	v_add_f32_e32 v222, v219, v220
	v_add_f32_e32 v213, v213, v214
	v_add_f32_e32 v219, 1.0, v227
	v_cmp_gt_f32_e32 vcc, s31, v219
	v_add_f32_e32 v227, v215, v216
	v_add_f32_e32 v216, v36, v225
	v_cndmask_b32_e64 v220, 0, 32, vcc
	v_ldexp_f32 v219, v219, v220
	v_log_f32_e32 v219, v219
	v_mul_f32_e64 v215, |v216|, s30
	v_exp_f32_e32 v215, v215
	v_add_f32_e32 v223, v223, v224
	v_mul_f32_e32 v214, 0x3f317217, v219
	v_fma_f32 v214, v219, s33, -v214
	v_fmac_f32_e32 v214, 0x3377d1cf, v219
	v_fmac_f32_e32 v214, 0x3f317217, v219
	v_cmp_lt_f32_e64 s[4:5], |v219|, s34
	v_add_f32_e32 v215, 1.0, v215
	v_add_f32_e32 v224, v217, v218
	v_cndmask_b32_e64 v214, v219, v214, s[4:5]
	v_cmp_gt_f32_e64 s[4:5], s31, v215
	v_add_f32_e32 v220, v35, v223
	v_mul_f32_e64 v219, |v220|, s30
	v_cndmask_b32_e64 v217, 0, 32, s[4:5]
	v_ldexp_f32 v215, v215, v217
	v_log_f32_e32 v218, v215
	v_cndmask_b32_e32 v215, 0, v212, vcc
	v_sub_f32_e32 v215, v214, v215
	v_exp_f32_e32 v219, v219
	v_mul_f32_e32 v214, 0x3f317217, v218
	v_fma_f32 v214, v218, s33, -v214
	v_fmac_f32_e32 v214, 0x3377d1cf, v218
	v_fmac_f32_e32 v214, 0x3f317217, v218
	v_cmp_lt_f32_e64 vcc, |v218|, s34
	v_add_f32_e32 v223, v34, v221
	v_mul_f32_e64 v221, |v223|, s30
	v_cndmask_b32_e32 v214, v218, v214, vcc
	v_add_f32_e32 v218, 1.0, v219
	v_cmp_gt_f32_e32 vcc, s31, v218
	v_exp_f32_e32 v221, v221
	v_mul_f32_e32 v213, 0xbfb8aa3b, v213
	v_cndmask_b32_e64 v219, 0, 32, vcc
	v_ldexp_f32 v218, v218, v219
	v_log_f32_e32 v218, v218
	v_cndmask_b32_e64 v219, 0, v212, s[4:5]
	v_sub_f32_e32 v214, v214, v219
	v_exp_f32_e32 v213, v213
	v_mul_f32_e32 v219, 0x3f317217, v218
	v_fma_f32 v219, v218, s33, -v219
	v_fmac_f32_e32 v219, 0x3377d1cf, v218
	v_fmac_f32_e32 v219, 0x3f317217, v218
	v_cmp_lt_f32_e64 s[4:5], |v218|, s34
	v_mul_f32_e32 v222, 0xbfb8aa3b, v222
	v_max_f32_e32 v217, 0, v226
	v_cndmask_b32_e64 v218, v218, v219, s[4:5]
	v_add_f32_e32 v219, 1.0, v221
	v_cmp_gt_f32_e64 s[4:5], s31, v219
	v_max_f32_e32 v216, 0, v216
	v_exp_f32_e32 v222, v222
	v_cndmask_b32_e64 v221, 0, 32, s[4:5]
	v_ldexp_f32 v219, v219, v221
	v_log_f32_e32 v225, v219
	v_cndmask_b32_e32 v219, 0, v212, vcc
	v_sub_f32_e32 v219, v218, v219
	v_max_f32_e32 v221, 0, v220
	v_mul_f32_e32 v218, 0x3f317217, v225
	v_fma_f32 v218, v225, s33, -v218
	v_fmac_f32_e32 v218, 0x3377d1cf, v225
	v_fmac_f32_e32 v218, 0x3f317217, v225
	v_cmp_lt_f32_e64 vcc, |v225|, s34
	v_cndmask_b32_e64 v220, 0, v212, s[4:5]
	v_pk_add_f32 v[214:215], v[216:217], v[214:215]
	v_cndmask_b32_e32 v218, v225, v218, vcc
	v_sub_f32_e32 v218, v218, v220
	v_max_f32_e32 v220, 0, v223
	v_mul_f32_e32 v223, 0xbfb8aa3b, v224
	v_mul_f32_e32 v224, 0xbfb8aa3b, v227
	v_exp_f32_e32 v224, v224
	v_exp_f32_e32 v223, v223
	v_pk_add_f32 v[218:219], v[220:221], v[218:219]
	v_add_f32_e32 v213, 1.0, v213
	v_pk_mul_f32 v[216:217], v[214:215], s[10:11]
	v_pk_mul_f32 v[214:215], v[218:219], s[8:9] neg_lo:[0,1] neg_hi:[0,1]
	v_rcp_f32_e32 v218, v213
	v_add_f32_e32 v213, 1.0, v224
	v_rcp_f32_e32 v219, v213
	v_add_f32_e32 v213, 1.0, v223
	v_rcp_f32_e32 v220, v213
	v_add_f32_e32 v213, 1.0, v222
	s_lshl_b64 s[4:5], s[12:13], 4
	v_rcp_f32_e32 v221, v213
	s_add_u32 s12, s24, s4
	s_addc_u32 s13, s25, s5
	s_add_u32 s4, s26, s4
	s_addc_u32 s5, s27, s5
	global_store_dwordx4 v201, v[218:221], s[12:13] sc1
	global_store_dwordx4 v201, v[214:217], s[4:5] sc1
	s_branch .LBB0_77
